# v52 plus the six simple P0 weight transposes issue both 16-load batches of an item before the first LDS write (32 loads in flight)
# baseline (speedup 1.0000x reference)
.LBB0_19:
	s_lshl_b32 s56, s16, 1
	s_lshl_b32 s57, s18, 1
	v_or_b32_e32 v6, s57, v36
	s_add_i32 s58, s56, 4
	s_add_i32 s59, s57, 4
	v_mov_b32_e32 v41, v7
	s_add_i32 s70, s57, 8
	v_lshlrev_b64 v[70:71], 13, v[6:7]
	v_or_b32_e32 v40, s58, v5
	v_or_b32_e32 v6, s59, v36
	v_mov_b32_e32 v39, v7
	v_or_b32_e32 v38, s56, v5
	s_add_i32 s72, s57, 12
	v_lshlrev_b64 v[40:41], 13, v[40:41]
	v_lshlrev_b64 v[72:73], 13, v[6:7]
	v_or_b32_e32 v6, s70, v36
	s_add_i32 s69, s56, 8
	s_add_i32 s71, s56, 12
	s_add_i32 s74, s57, 16
	v_lshlrev_b64 v[38:39], 13, v[38:39]
	v_lshl_add_u64 v[70:71], v[34:35], 0, v[70:71]
	v_lshl_add_u64 v[40:41], v[34:35], 0, v[40:41]
	v_lshlrev_b64 v[74:75], 13, v[6:7]
	v_or_b32_e32 v6, s72, v36
	v_mov_b32_e32 v43, v7
	v_mov_b32_e32 v45, v7
	s_add_i32 s76, s57, 20
	v_or_b32_e32 v42, s69, v5
	v_or_b32_e32 v44, s71, v5
	v_lshl_add_u64 v[38:39], v[34:35], 0, v[38:39]
	v_lshl_add_u64 v[72:73], v[34:35], 0, v[72:73]
	global_load_dword v37, v[70:71], off
	global_load_dword v69, v[38:39], off
	global_load_dword v86, v[72:73], off
	global_load_dword v87, v[40:41], off
	v_lshlrev_b64 v[40:41], 13, v[6:7]
	v_or_b32_e32 v6, s74, v36
	s_add_i32 s73, s56, 16
	s_add_i32 s75, s56, 20
	s_add_i32 s78, s57, 24
	v_lshlrev_b64 v[42:43], 13, v[42:43]
	v_lshlrev_b64 v[44:45], 13, v[44:45]
	v_lshl_add_u64 v[38:39], v[34:35], 0, v[74:75]
	v_lshl_add_u64 v[40:41], v[34:35], 0, v[40:41]
	v_lshlrev_b64 v[70:71], 13, v[6:7]
	v_or_b32_e32 v6, s76, v36
	v_mov_b32_e32 v47, v7
	v_mov_b32_e32 v49, v7
	s_add_i32 s77, s56, 24
	s_add_i32 s79, s56, 28
	s_add_i32 s80, s57, 28
	v_or_b32_e32 v46, s73, v5
	v_or_b32_e32 v48, s75, v5
	v_lshl_add_u64 v[42:43], v[34:35], 0, v[42:43]
	v_lshl_add_u64 v[44:45], v[34:35], 0, v[44:45]
	global_load_dword v88, v[38:39], off
	global_load_dword v89, v[42:43], off
	global_load_dword v90, v[40:41], off
	global_load_dword v91, v[44:45], off
	v_lshlrev_b64 v[40:41], 13, v[6:7]
	v_or_b32_e32 v6, s78, v36
	v_mov_b32_e32 v51, v7
	v_mov_b32_e32 v53, v7
	v_or_b32_e32 v50, s77, v5
	v_or_b32_e32 v52, s79, v5
	v_lshlrev_b64 v[46:47], 13, v[46:47]
	v_lshlrev_b64 v[48:49], 13, v[48:49]
	v_lshl_add_u64 v[38:39], v[34:35], 0, v[70:71]
	v_lshl_add_u64 v[40:41], v[34:35], 0, v[40:41]
	v_lshlrev_b64 v[42:43], 13, v[6:7]
	v_or_b32_e32 v6, s80, v36
	v_lshlrev_b64 v[50:51], 13, v[50:51]
	v_lshlrev_b64 v[52:53], 13, v[52:53]
	v_lshl_add_u64 v[46:47], v[34:35], 0, v[46:47]
	v_lshl_add_u64 v[48:49], v[34:35], 0, v[48:49]
	global_load_dword v92, v[38:39], off
	global_load_dword v93, v[46:47], off
	global_load_dword v94, v[40:41], off
	global_load_dword v95, v[48:49], off
	v_lshl_add_u64 v[38:39], v[34:35], 0, v[42:43]
	v_lshlrev_b64 v[40:41], 13, v[6:7]
	v_lshl_add_u64 v[50:51], v[34:35], 0, v[50:51]
	v_lshl_add_u64 v[52:53], v[34:35], 0, v[52:53]
	v_lshl_add_u64 v[40:41], v[34:35], 0, v[40:41]
	global_load_dword v6, v[38:39], off
	global_load_dword v96, v[50:51], off
	global_load_dword v97, v[40:41], off
	global_load_dword v98, v[52:53], off
	v_or_b32_e32 v40, s56, v1
	v_or_b32_e32 v38, s57, v2
	s_add_i32 s18, s18, 16
	s_add_i32 s16, s16, 16
	s_add_i32 s19, s19, -16
	v_mad_u64_u32 v[38:39], s[56:57], v38, s13, v[4:5]
	v_mad_u64_u32 v[40:41], s[56:57], v40, s13, v[4:5]
	v_or_b32_e32 v39, s58, v1
	v_or_b32_e32 v41, s59, v2
	v_or_b32_e32 v48, s69, v1
	v_or_b32_e32 v46, s70, v2
	v_or_b32_e32 v52, s71, v1
	v_or_b32_e32 v50, s72, v2
	v_or_b32_e32 v72, s73, v1
	v_or_b32_e32 v70, s74, v2
	v_or_b32_e32 v76, s75, v1
	v_or_b32_e32 v74, s76, v2
	v_or_b32_e32 v80, s77, v1
	v_or_b32_e32 v78, s78, v2
	v_or_b32_e32 v84, s79, v1
	v_or_b32_e32 v82, s80, v2
	s_cmp_lg_u32 s19, 0
	v_mad_u64_u32 v[42:43], s[56:57], v41, s13, v[4:5]
	v_mad_u64_u32 v[44:45], s[56:57], v39, s13, v[4:5]
	v_mad_u64_u32 v[46:47], s[56:57], v46, s13, v[4:5]
	v_mad_u64_u32 v[48:49], s[56:57], v48, s13, v[4:5]
	v_mad_u64_u32 v[50:51], s[56:57], v50, s13, v[4:5]
	v_mad_u64_u32 v[52:53], s[56:57], v52, s13, v[4:5]
	v_mad_u64_u32 v[70:71], s[56:57], v70, s13, v[4:5]
	v_mad_u64_u32 v[72:73], s[56:57], v72, s13, v[4:5]
	v_mad_u64_u32 v[74:75], s[56:57], v74, s13, v[4:5]
	v_mad_u64_u32 v[76:77], s[56:57], v76, s13, v[4:5]
	v_mad_u64_u32 v[78:79], s[56:57], v78, s13, v[4:5]
	v_mad_u64_u32 v[80:81], s[56:57], v80, s13, v[4:5]
	v_mad_u64_u32 v[82:83], s[56:57], v82, s13, v[4:5]
	v_mad_u64_u32 v[84:85], s[56:57], v84, s13, v[4:5]
	v_mov_b32_e32 v107, v7
	s_lshl_b32 s56, s16, 1
	s_lshl_b32 s57, s18, 1
	v_or_b32_e32 v106, s57, v36
	s_add_i32 s58, s56, 4
	s_add_i32 s59, s57, 4
	v_mov_b32_e32 v141, v107
	s_add_i32 s70, s57, 8
	v_lshlrev_b64 v[170:171], 13, v[106:107]
	v_or_b32_e32 v140, s58, v5
	v_or_b32_e32 v106, s59, v36
	v_mov_b32_e32 v139, v107
	v_or_b32_e32 v138, s56, v5
	s_add_i32 s72, s57, 12
	v_lshlrev_b64 v[140:141], 13, v[140:141]
	v_lshlrev_b64 v[172:173], 13, v[106:107]
	v_or_b32_e32 v106, s70, v36
	s_add_i32 s69, s56, 8
	s_add_i32 s71, s56, 12
	s_add_i32 s74, s57, 16
	v_lshlrev_b64 v[138:139], 13, v[138:139]
	v_lshl_add_u64 v[170:171], v[34:35], 0, v[170:171]
	v_lshl_add_u64 v[140:141], v[34:35], 0, v[140:141]
	v_lshlrev_b64 v[174:175], 13, v[106:107]
	v_or_b32_e32 v106, s72, v36
	v_mov_b32_e32 v143, v107
	v_mov_b32_e32 v145, v107
	s_add_i32 s76, s57, 20
	v_or_b32_e32 v142, s69, v5
	v_or_b32_e32 v144, s71, v5
	v_lshl_add_u64 v[138:139], v[34:35], 0, v[138:139]
	v_lshl_add_u64 v[172:173], v[34:35], 0, v[172:173]
	global_load_dword v137, v[170:171], off
	global_load_dword v169, v[138:139], off
	global_load_dword v186, v[172:173], off
	global_load_dword v187, v[140:141], off
	v_lshlrev_b64 v[140:141], 13, v[106:107]
	v_or_b32_e32 v106, s74, v36
	s_add_i32 s73, s56, 16
	s_add_i32 s75, s56, 20
	s_add_i32 s78, s57, 24
	v_lshlrev_b64 v[142:143], 13, v[142:143]
	v_lshlrev_b64 v[144:145], 13, v[144:145]
	v_lshl_add_u64 v[138:139], v[34:35], 0, v[174:175]
	v_lshl_add_u64 v[140:141], v[34:35], 0, v[140:141]
	v_lshlrev_b64 v[170:171], 13, v[106:107]
	v_or_b32_e32 v106, s76, v36
	v_mov_b32_e32 v147, v107
	v_mov_b32_e32 v149, v107
	s_add_i32 s77, s56, 24
	s_add_i32 s79, s56, 28
	s_add_i32 s80, s57, 28
	v_or_b32_e32 v146, s73, v5
	v_or_b32_e32 v148, s75, v5
	v_lshl_add_u64 v[142:143], v[34:35], 0, v[142:143]
	v_lshl_add_u64 v[144:145], v[34:35], 0, v[144:145]
	global_load_dword v188, v[138:139], off
	global_load_dword v189, v[142:143], off
	global_load_dword v190, v[140:141], off
	global_load_dword v191, v[144:145], off
	v_lshlrev_b64 v[140:141], 13, v[106:107]
	v_or_b32_e32 v106, s78, v36
	v_mov_b32_e32 v151, v107
	v_mov_b32_e32 v153, v107
	v_or_b32_e32 v150, s77, v5
	v_or_b32_e32 v152, s79, v5
	v_lshlrev_b64 v[146:147], 13, v[146:147]
	v_lshlrev_b64 v[148:149], 13, v[148:149]
	v_lshl_add_u64 v[138:139], v[34:35], 0, v[170:171]
	v_lshl_add_u64 v[140:141], v[34:35], 0, v[140:141]
	v_lshlrev_b64 v[142:143], 13, v[106:107]
	v_or_b32_e32 v106, s80, v36
	v_lshlrev_b64 v[150:151], 13, v[150:151]
	v_lshlrev_b64 v[152:153], 13, v[152:153]
	v_lshl_add_u64 v[146:147], v[34:35], 0, v[146:147]
	v_lshl_add_u64 v[148:149], v[34:35], 0, v[148:149]
	global_load_dword v192, v[138:139], off
	global_load_dword v193, v[146:147], off
	global_load_dword v194, v[140:141], off
	global_load_dword v195, v[148:149], off
	v_lshl_add_u64 v[138:139], v[34:35], 0, v[142:143]
	v_lshlrev_b64 v[140:141], 13, v[106:107]
	v_lshl_add_u64 v[150:151], v[34:35], 0, v[150:151]
	v_lshl_add_u64 v[152:153], v[34:35], 0, v[152:153]
	v_lshl_add_u64 v[140:141], v[34:35], 0, v[140:141]
	global_load_dword v106, v[138:139], off
	global_load_dword v196, v[150:151], off
	global_load_dword v197, v[140:141], off
	global_load_dword v198, v[152:153], off
	v_or_b32_e32 v140, s56, v1
	v_or_b32_e32 v138, s57, v2
	s_add_i32 s18, s18, 16
	s_add_i32 s16, s16, 16
	s_add_i32 s19, s19, -16
	v_mad_u64_u32 v[138:139], s[56:57], v138, s13, v[4:5]
	v_mad_u64_u32 v[140:141], s[56:57], v140, s13, v[4:5]
	v_or_b32_e32 v139, s58, v1
	v_or_b32_e32 v141, s59, v2
	v_or_b32_e32 v148, s69, v1
	v_or_b32_e32 v146, s70, v2
	v_or_b32_e32 v152, s71, v1
	v_or_b32_e32 v150, s72, v2
	v_or_b32_e32 v172, s73, v1
	v_or_b32_e32 v170, s74, v2
	v_or_b32_e32 v176, s75, v1
	v_or_b32_e32 v174, s76, v2
	v_or_b32_e32 v180, s77, v1
	v_or_b32_e32 v178, s78, v2
	v_or_b32_e32 v184, s79, v1
	v_or_b32_e32 v182, s80, v2
	s_cmp_lg_u32 s19, 0
	v_mad_u64_u32 v[142:143], s[56:57], v141, s13, v[4:5]
	v_mad_u64_u32 v[144:145], s[56:57], v139, s13, v[4:5]
	v_mad_u64_u32 v[146:147], s[56:57], v146, s13, v[4:5]
	v_mad_u64_u32 v[148:149], s[56:57], v148, s13, v[4:5]
	v_mad_u64_u32 v[150:151], s[56:57], v150, s13, v[4:5]
	v_mad_u64_u32 v[152:153], s[56:57], v152, s13, v[4:5]
	v_mad_u64_u32 v[170:171], s[56:57], v170, s13, v[4:5]
	v_mad_u64_u32 v[172:173], s[56:57], v172, s13, v[4:5]
	v_mad_u64_u32 v[174:175], s[56:57], v174, s13, v[4:5]
	v_mad_u64_u32 v[176:177], s[56:57], v176, s13, v[4:5]
	v_mad_u64_u32 v[178:179], s[56:57], v178, s13, v[4:5]
	v_mad_u64_u32 v[180:181], s[56:57], v180, s13, v[4:5]
	v_mad_u64_u32 v[182:183], s[56:57], v182, s13, v[4:5]
	v_mad_u64_u32 v[184:185], s[56:57], v184, s13, v[4:5]
	s_waitcnt vmcnt(16)
	ds_write_b32 v38, v37
	ds_write_b32 v40, v69
	ds_write_b32 v42, v86
	ds_write_b32 v44, v87
	ds_write_b32 v46, v88
	ds_write_b32 v48, v89
	ds_write_b32 v50, v90
	ds_write_b32 v52, v91
	ds_write_b32 v70, v92
	ds_write_b32 v72, v93
	ds_write_b32 v74, v94
	ds_write_b32 v76, v95
	ds_write_b32 v78, v6
	ds_write_b32 v80, v96
	ds_write_b32 v82, v97
	ds_write_b32 v84, v98
	s_waitcnt vmcnt(0)
	ds_write_b32 v138, v137
	ds_write_b32 v140, v169
	ds_write_b32 v142, v186
	ds_write_b32 v144, v187
	ds_write_b32 v146, v188
	ds_write_b32 v148, v189
	ds_write_b32 v150, v190
	ds_write_b32 v152, v191
	ds_write_b32 v170, v192
	ds_write_b32 v172, v193
	ds_write_b32 v174, v194
	ds_write_b32 v176, v195
	ds_write_b32 v178, v106
	ds_write_b32 v180, v196
	ds_write_b32 v182, v197
	ds_write_b32 v184, v198
	s_waitcnt lgkmcnt(0)
	ds_read_b32 v5, v55
	ds_read_b32 v6, v55 offset:132
	ds_read_b32 v35, v55 offset:264
	ds_read_b32 v36, v55 offset:396
	ds_read_b32 v37, v55 offset:528
	ds_read_b32 v40, v55 offset:660
	ds_read_b32 v41, v55 offset:792
	ds_read_b32 v42, v55 offset:924
	s_waitcnt lgkmcnt(7)
	v_bfe_u32 v34, v5, 16, 1
	v_add3_u32 v5, v5, v34, s62
	s_waitcnt lgkmcnt(6)
	v_bfe_u32 v34, v6, 16, 1
	v_lshrrev_b32_e32 v5, 16, v5
	v_add3_u32 v6, v6, v34, s62
	v_and_or_b32 v34, v6, s63, v5
	s_waitcnt lgkmcnt(5)
	v_bfe_u32 v5, v35, 16, 1
	v_add3_u32 v5, v35, v5, s62
	s_waitcnt lgkmcnt(4)
	v_bfe_u32 v6, v36, 16, 1
	v_lshrrev_b32_e32 v5, 16, v5
	v_add3_u32 v6, v36, v6, s62
	v_and_or_b32 v35, v6, s63, v5
	s_waitcnt lgkmcnt(3)
	v_bfe_u32 v5, v37, 16, 1
	v_add3_u32 v5, v37, v5, s62
	s_waitcnt lgkmcnt(2)
	v_bfe_u32 v6, v40, 16, 1
	v_lshrrev_b32_e32 v5, 16, v5
	v_add3_u32 v6, v40, v6, s62
	v_and_or_b32 v36, v6, s63, v5
	s_waitcnt lgkmcnt(1)
	v_bfe_u32 v5, v41, 16, 1
	v_add3_u32 v5, v41, v5, s62
	s_waitcnt lgkmcnt(0)
	v_bfe_u32 v6, v42, 16, 1
	v_lshrrev_b32_e32 v5, 16, v5
	v_add3_u32 v6, v42, v6, s62
	s_lshl_b32 s16, s5, 1
	v_and_or_b32 v37, v6, s63, v5
	v_or_b32_e32 v5, s4, v33
	v_lshl_add_u64 v[38:39], v[8:9], 0, s[16:17]
	v_lshlrev_b32_e32 v6, 14, v5
	v_lshl_add_u64 v[40:41], v[38:39], 0, v[6:7]
	flat_store_dwordx4 v[40:41], v[34:37]
	ds_read_b32 v5, v55 offset:32
	ds_read_b32 v6, v55 offset:164
	ds_read_b32 v35, v55 offset:296
	ds_read_b32 v36, v55 offset:428
	ds_read_b32 v37, v55 offset:560
	ds_read_b32 v40, v55 offset:692
	ds_read_b32 v41, v55 offset:824
	ds_read_b32 v42, v55 offset:956
	s_waitcnt lgkmcnt(0)
	v_bfe_u32 v34, v5, 16, 1
	v_add3_u32 v5, v5, v34, s62
	v_bfe_u32 v34, v6, 16, 1
	v_lshrrev_b32_e32 v5, 16, v5
	v_add3_u32 v6, v6, v34, s62
	v_and_or_b32 v34, v6, s63, v5
	v_bfe_u32 v5, v35, 16, 1
	v_add3_u32 v5, v35, v5, s62
	v_bfe_u32 v6, v36, 16, 1
	v_lshrrev_b32_e32 v5, 16, v5
	v_add3_u32 v6, v36, v6, s62
	v_and_or_b32 v35, v6, s63, v5
	v_bfe_u32 v5, v37, 16, 1
	v_add3_u32 v5, v37, v5, s62
	v_bfe_u32 v6, v40, 16, 1
	v_lshrrev_b32_e32 v5, 16, v5
	v_add3_u32 v6, v40, v6, s62
	v_and_or_b32 v36, v6, s63, v5
	v_bfe_u32 v5, v41, 16, 1
	v_add3_u32 v5, v41, v5, s62
	v_bfe_u32 v6, v42, 16, 1
	v_lshrrev_b32_e32 v5, 16, v5
	v_add3_u32 v6, v42, v6, s62
	v_and_or_b32 v37, v6, s63, v5
	v_or_b32_e32 v5, s4, v56
	v_lshlrev_b32_e32 v6, 14, v5
	v_lshl_add_u64 v[40:41], v[38:39], 0, v[6:7]
	flat_store_dwordx4 v[40:41], v[34:37]
	ds_read_b32 v5, v55 offset:64
	ds_read_b32 v6, v55 offset:196
	ds_read_b32 v35, v55 offset:328
	ds_read_b32 v36, v55 offset:460
	ds_read_b32 v37, v55 offset:592
	ds_read_b32 v40, v55 offset:724
	ds_read_b32 v41, v55 offset:856
	ds_read_b32 v42, v55 offset:988
	s_waitcnt lgkmcnt(0)
	v_bfe_u32 v34, v5, 16, 1
	v_add3_u32 v5, v5, v34, s62
	v_bfe_u32 v34, v6, 16, 1
	v_lshrrev_b32_e32 v5, 16, v5
	v_add3_u32 v6, v6, v34, s62
	v_and_or_b32 v34, v6, s63, v5
	v_bfe_u32 v5, v35, 16, 1
	v_add3_u32 v5, v35, v5, s62
	v_bfe_u32 v6, v36, 16, 1
	v_lshrrev_b32_e32 v5, 16, v5
	v_add3_u32 v6, v36, v6, s62
	v_and_or_b32 v35, v6, s63, v5
	v_bfe_u32 v5, v37, 16, 1
	v_add3_u32 v5, v37, v5, s62
	v_bfe_u32 v6, v40, 16, 1
	v_lshrrev_b32_e32 v5, 16, v5
	v_add3_u32 v6, v40, v6, s62
	v_and_or_b32 v36, v6, s63, v5
	v_bfe_u32 v5, v41, 16, 1
	v_add3_u32 v5, v41, v5, s62
	v_bfe_u32 v6, v42, 16, 1
	v_lshrrev_b32_e32 v5, 16, v5
	v_add3_u32 v6, v42, v6, s62
	v_and_or_b32 v37, v6, s63, v5
	v_or_b32_e32 v5, s4, v57
	v_lshlrev_b32_e32 v6, 14, v5
	v_lshl_add_u64 v[40:41], v[38:39], 0, v[6:7]
	flat_store_dwordx4 v[40:41], v[34:37]
	ds_read_b32 v5, v55 offset:96
	ds_read_b32 v6, v55 offset:228
	ds_read_b32 v35, v55 offset:360
	ds_read_b32 v36, v55 offset:492
	ds_read_b32 v37, v55 offset:624
	ds_read_b32 v40, v55 offset:756
	ds_read_b32 v41, v55 offset:888
	ds_read_b32 v42, v55 offset:1020
	s_waitcnt lgkmcnt(0)
	v_bfe_u32 v34, v5, 16, 1
	v_add3_u32 v5, v5, v34, s62
	v_bfe_u32 v34, v6, 16, 1
	v_lshrrev_b32_e32 v5, 16, v5
	v_add3_u32 v6, v6, v34, s62
	v_and_or_b32 v34, v6, s63, v5
	v_bfe_u32 v5, v35, 16, 1
	v_add3_u32 v5, v35, v5, s62
	v_bfe_u32 v6, v36, 16, 1
	v_lshrrev_b32_e32 v5, 16, v5
	v_add3_u32 v6, v36, v6, s62
	v_and_or_b32 v35, v6, s63, v5
	v_bfe_u32 v5, v37, 16, 1
	v_add3_u32 v5, v37, v5, s62
	v_bfe_u32 v6, v40, 16, 1
	v_lshrrev_b32_e32 v5, 16, v5
	v_add3_u32 v6, v40, v6, s62
	v_and_or_b32 v36, v6, s63, v5
	v_bfe_u32 v5, v41, 16, 1
	v_add3_u32 v5, v41, v5, s62
	v_bfe_u32 v6, v42, 16, 1
	v_lshrrev_b32_e32 v5, 16, v5
	v_add3_u32 v6, v42, v6, s62
	v_and_or_b32 v37, v6, s63, v5
	v_or_b32_e32 v5, s4, v58
	v_lshlrev_b32_e32 v6, 14, v5
	v_lshl_add_u64 v[38:39], v[38:39], 0, v[6:7]
	flat_store_dwordx4 v[38:39], v[34:37]
	s_waitcnt lgkmcnt(0)
	s_mov_b64 s[4:5], 0

.LBB0_44:
	s_lshl_b32 s56, s16, 1
	s_lshl_b32 s57, s18, 1
	v_or_b32_e32 v6, s57, v36
	s_add_i32 s58, s56, 4
	s_add_i32 s59, s57, 4
	v_mov_b32_e32 v41, v7
	s_add_i32 s70, s57, 8
	v_lshlrev_b64 v[70:71], 13, v[6:7]
	v_or_b32_e32 v40, s58, v5
	v_or_b32_e32 v6, s59, v36
	v_mov_b32_e32 v39, v7
	v_or_b32_e32 v38, s56, v5
	s_add_i32 s72, s57, 12
	v_lshlrev_b64 v[40:41], 13, v[40:41]
	v_lshlrev_b64 v[72:73], 13, v[6:7]
	v_or_b32_e32 v6, s70, v36
	s_add_i32 s69, s56, 8
	s_add_i32 s71, s56, 12
	s_add_i32 s74, s57, 16
	v_lshlrev_b64 v[38:39], 13, v[38:39]
	v_lshl_add_u64 v[70:71], v[34:35], 0, v[70:71]
	v_lshl_add_u64 v[40:41], v[34:35], 0, v[40:41]
	v_lshlrev_b64 v[74:75], 13, v[6:7]
	v_or_b32_e32 v6, s72, v36
	v_mov_b32_e32 v43, v7
	v_mov_b32_e32 v45, v7
	s_add_i32 s76, s57, 20
	v_or_b32_e32 v42, s69, v5
	v_or_b32_e32 v44, s71, v5
	v_lshl_add_u64 v[38:39], v[34:35], 0, v[38:39]
	v_lshl_add_u64 v[72:73], v[34:35], 0, v[72:73]
	global_load_dword v37, v[70:71], off
	global_load_dword v69, v[38:39], off
	global_load_dword v86, v[72:73], off
	global_load_dword v87, v[40:41], off
	v_lshlrev_b64 v[40:41], 13, v[6:7]
	v_or_b32_e32 v6, s74, v36
	s_add_i32 s73, s56, 16
	s_add_i32 s75, s56, 20
	s_add_i32 s78, s57, 24
	v_lshlrev_b64 v[42:43], 13, v[42:43]
	v_lshlrev_b64 v[44:45], 13, v[44:45]
	v_lshl_add_u64 v[38:39], v[34:35], 0, v[74:75]
	v_lshl_add_u64 v[40:41], v[34:35], 0, v[40:41]
	v_lshlrev_b64 v[70:71], 13, v[6:7]
	v_or_b32_e32 v6, s76, v36
	v_mov_b32_e32 v47, v7
	v_mov_b32_e32 v49, v7
	s_add_i32 s77, s56, 24
	s_add_i32 s79, s56, 28
	s_add_i32 s80, s57, 28
	v_or_b32_e32 v46, s73, v5
	v_or_b32_e32 v48, s75, v5
	v_lshl_add_u64 v[42:43], v[34:35], 0, v[42:43]
	v_lshl_add_u64 v[44:45], v[34:35], 0, v[44:45]
	global_load_dword v88, v[38:39], off
	global_load_dword v89, v[42:43], off
	global_load_dword v90, v[40:41], off
	global_load_dword v91, v[44:45], off
	v_lshlrev_b64 v[40:41], 13, v[6:7]
	v_or_b32_e32 v6, s78, v36
	v_mov_b32_e32 v51, v7
	v_mov_b32_e32 v53, v7
	v_or_b32_e32 v50, s77, v5
	v_or_b32_e32 v52, s79, v5
	v_lshlrev_b64 v[46:47], 13, v[46:47]
	v_lshlrev_b64 v[48:49], 13, v[48:49]
	v_lshl_add_u64 v[38:39], v[34:35], 0, v[70:71]
	v_lshl_add_u64 v[40:41], v[34:35], 0, v[40:41]
	v_lshlrev_b64 v[42:43], 13, v[6:7]
	v_or_b32_e32 v6, s80, v36
	v_lshlrev_b64 v[50:51], 13, v[50:51]
	v_lshlrev_b64 v[52:53], 13, v[52:53]
	v_lshl_add_u64 v[46:47], v[34:35], 0, v[46:47]
	v_lshl_add_u64 v[48:49], v[34:35], 0, v[48:49]
	global_load_dword v92, v[38:39], off
	global_load_dword v93, v[46:47], off
	global_load_dword v94, v[40:41], off
	global_load_dword v95, v[48:49], off
	v_lshl_add_u64 v[38:39], v[34:35], 0, v[42:43]
	v_lshlrev_b64 v[40:41], 13, v[6:7]
	v_lshl_add_u64 v[50:51], v[34:35], 0, v[50:51]
	v_lshl_add_u64 v[52:53], v[34:35], 0, v[52:53]
	v_lshl_add_u64 v[40:41], v[34:35], 0, v[40:41]
	global_load_dword v6, v[38:39], off
	global_load_dword v96, v[50:51], off
	global_load_dword v97, v[40:41], off
	global_load_dword v98, v[52:53], off
	v_or_b32_e32 v40, s56, v1
	v_or_b32_e32 v38, s57, v2
	s_add_i32 s18, s18, 16
	s_add_i32 s16, s16, 16
	s_add_i32 s19, s19, -16
	v_mad_u64_u32 v[38:39], s[56:57], v38, s13, v[4:5]
	v_mad_u64_u32 v[40:41], s[56:57], v40, s13, v[4:5]
	v_or_b32_e32 v39, s58, v1
	v_or_b32_e32 v41, s59, v2
	v_or_b32_e32 v48, s69, v1
	v_or_b32_e32 v46, s70, v2
	v_or_b32_e32 v52, s71, v1
	v_or_b32_e32 v50, s72, v2
	v_or_b32_e32 v72, s73, v1
	v_or_b32_e32 v70, s74, v2
	v_or_b32_e32 v76, s75, v1
	v_or_b32_e32 v74, s76, v2
	v_or_b32_e32 v80, s77, v1
	v_or_b32_e32 v78, s78, v2
	v_or_b32_e32 v84, s79, v1
	v_or_b32_e32 v82, s80, v2
	s_cmp_lg_u32 s19, 0
	v_mad_u64_u32 v[42:43], s[56:57], v41, s13, v[4:5]
	v_mad_u64_u32 v[44:45], s[56:57], v39, s13, v[4:5]
	v_mad_u64_u32 v[46:47], s[56:57], v46, s13, v[4:5]
	v_mad_u64_u32 v[48:49], s[56:57], v48, s13, v[4:5]
	v_mad_u64_u32 v[50:51], s[56:57], v50, s13, v[4:5]
	v_mad_u64_u32 v[52:53], s[56:57], v52, s13, v[4:5]
	v_mad_u64_u32 v[70:71], s[56:57], v70, s13, v[4:5]
	v_mad_u64_u32 v[72:73], s[56:57], v72, s13, v[4:5]
	v_mad_u64_u32 v[74:75], s[56:57], v74, s13, v[4:5]
	v_mad_u64_u32 v[76:77], s[56:57], v76, s13, v[4:5]
	v_mad_u64_u32 v[78:79], s[56:57], v78, s13, v[4:5]
	v_mad_u64_u32 v[80:81], s[56:57], v80, s13, v[4:5]
	v_mad_u64_u32 v[82:83], s[56:57], v82, s13, v[4:5]
	v_mad_u64_u32 v[84:85], s[56:57], v84, s13, v[4:5]
	v_mov_b32_e32 v107, v7
	s_lshl_b32 s56, s16, 1
	s_lshl_b32 s57, s18, 1
	v_or_b32_e32 v106, s57, v36
	s_add_i32 s58, s56, 4
	s_add_i32 s59, s57, 4
	v_mov_b32_e32 v141, v107
	s_add_i32 s70, s57, 8
	v_lshlrev_b64 v[170:171], 13, v[106:107]
	v_or_b32_e32 v140, s58, v5
	v_or_b32_e32 v106, s59, v36
	v_mov_b32_e32 v139, v107
	v_or_b32_e32 v138, s56, v5
	s_add_i32 s72, s57, 12
	v_lshlrev_b64 v[140:141], 13, v[140:141]
	v_lshlrev_b64 v[172:173], 13, v[106:107]
	v_or_b32_e32 v106, s70, v36
	s_add_i32 s69, s56, 8
	s_add_i32 s71, s56, 12
	s_add_i32 s74, s57, 16
	v_lshlrev_b64 v[138:139], 13, v[138:139]
	v_lshl_add_u64 v[170:171], v[34:35], 0, v[170:171]
	v_lshl_add_u64 v[140:141], v[34:35], 0, v[140:141]
	v_lshlrev_b64 v[174:175], 13, v[106:107]
	v_or_b32_e32 v106, s72, v36
	v_mov_b32_e32 v143, v107
	v_mov_b32_e32 v145, v107
	s_add_i32 s76, s57, 20
	v_or_b32_e32 v142, s69, v5
	v_or_b32_e32 v144, s71, v5
	v_lshl_add_u64 v[138:139], v[34:35], 0, v[138:139]
	v_lshl_add_u64 v[172:173], v[34:35], 0, v[172:173]
	global_load_dword v137, v[170:171], off
	global_load_dword v169, v[138:139], off
	global_load_dword v186, v[172:173], off
	global_load_dword v187, v[140:141], off
	v_lshlrev_b64 v[140:141], 13, v[106:107]
	v_or_b32_e32 v106, s74, v36
	s_add_i32 s73, s56, 16
	s_add_i32 s75, s56, 20
	s_add_i32 s78, s57, 24
	v_lshlrev_b64 v[142:143], 13, v[142:143]
	v_lshlrev_b64 v[144:145], 13, v[144:145]
	v_lshl_add_u64 v[138:139], v[34:35], 0, v[174:175]
	v_lshl_add_u64 v[140:141], v[34:35], 0, v[140:141]
	v_lshlrev_b64 v[170:171], 13, v[106:107]
	v_or_b32_e32 v106, s76, v36
	v_mov_b32_e32 v147, v107
	v_mov_b32_e32 v149, v107
	s_add_i32 s77, s56, 24
	s_add_i32 s79, s56, 28
	s_add_i32 s80, s57, 28
	v_or_b32_e32 v146, s73, v5
	v_or_b32_e32 v148, s75, v5
	v_lshl_add_u64 v[142:143], v[34:35], 0, v[142:143]
	v_lshl_add_u64 v[144:145], v[34:35], 0, v[144:145]
	global_load_dword v188, v[138:139], off
	global_load_dword v189, v[142:143], off
	global_load_dword v190, v[140:141], off
	global_load_dword v191, v[144:145], off
	v_lshlrev_b64 v[140:141], 13, v[106:107]
	v_or_b32_e32 v106, s78, v36
	v_mov_b32_e32 v151, v107
	v_mov_b32_e32 v153, v107
	v_or_b32_e32 v150, s77, v5
	v_or_b32_e32 v152, s79, v5
	v_lshlrev_b64 v[146:147], 13, v[146:147]
	v_lshlrev_b64 v[148:149], 13, v[148:149]
	v_lshl_add_u64 v[138:139], v[34:35], 0, v[170:171]
	v_lshl_add_u64 v[140:141], v[34:35], 0, v[140:141]
	v_lshlrev_b64 v[142:143], 13, v[106:107]
	v_or_b32_e32 v106, s80, v36
	v_lshlrev_b64 v[150:151], 13, v[150:151]
	v_lshlrev_b64 v[152:153], 13, v[152:153]
	v_lshl_add_u64 v[146:147], v[34:35], 0, v[146:147]
	v_lshl_add_u64 v[148:149], v[34:35], 0, v[148:149]
	global_load_dword v192, v[138:139], off
	global_load_dword v193, v[146:147], off
	global_load_dword v194, v[140:141], off
	global_load_dword v195, v[148:149], off
	v_lshl_add_u64 v[138:139], v[34:35], 0, v[142:143]
	v_lshlrev_b64 v[140:141], 13, v[106:107]
	v_lshl_add_u64 v[150:151], v[34:35], 0, v[150:151]
	v_lshl_add_u64 v[152:153], v[34:35], 0, v[152:153]
	v_lshl_add_u64 v[140:141], v[34:35], 0, v[140:141]
	global_load_dword v106, v[138:139], off
	global_load_dword v196, v[150:151], off
	global_load_dword v197, v[140:141], off
	global_load_dword v198, v[152:153], off
	v_or_b32_e32 v140, s56, v1
	v_or_b32_e32 v138, s57, v2
	s_add_i32 s18, s18, 16
	s_add_i32 s16, s16, 16
	s_add_i32 s19, s19, -16
	v_mad_u64_u32 v[138:139], s[56:57], v138, s13, v[4:5]
	v_mad_u64_u32 v[140:141], s[56:57], v140, s13, v[4:5]
	v_or_b32_e32 v139, s58, v1
	v_or_b32_e32 v141, s59, v2
	v_or_b32_e32 v148, s69, v1
	v_or_b32_e32 v146, s70, v2
	v_or_b32_e32 v152, s71, v1
	v_or_b32_e32 v150, s72, v2
	v_or_b32_e32 v172, s73, v1
	v_or_b32_e32 v170, s74, v2
	v_or_b32_e32 v176, s75, v1
	v_or_b32_e32 v174, s76, v2
	v_or_b32_e32 v180, s77, v1
	v_or_b32_e32 v178, s78, v2
	v_or_b32_e32 v184, s79, v1
	v_or_b32_e32 v182, s80, v2
	s_cmp_lg_u32 s19, 0
	v_mad_u64_u32 v[142:143], s[56:57], v141, s13, v[4:5]
	v_mad_u64_u32 v[144:145], s[56:57], v139, s13, v[4:5]
	v_mad_u64_u32 v[146:147], s[56:57], v146, s13, v[4:5]
	v_mad_u64_u32 v[148:149], s[56:57], v148, s13, v[4:5]
	v_mad_u64_u32 v[150:151], s[56:57], v150, s13, v[4:5]
	v_mad_u64_u32 v[152:153], s[56:57], v152, s13, v[4:5]
	v_mad_u64_u32 v[170:171], s[56:57], v170, s13, v[4:5]
	v_mad_u64_u32 v[172:173], s[56:57], v172, s13, v[4:5]
	v_mad_u64_u32 v[174:175], s[56:57], v174, s13, v[4:5]
	v_mad_u64_u32 v[176:177], s[56:57], v176, s13, v[4:5]
	v_mad_u64_u32 v[178:179], s[56:57], v178, s13, v[4:5]
	v_mad_u64_u32 v[180:181], s[56:57], v180, s13, v[4:5]
	v_mad_u64_u32 v[182:183], s[56:57], v182, s13, v[4:5]
	v_mad_u64_u32 v[184:185], s[56:57], v184, s13, v[4:5]
	s_waitcnt vmcnt(16)
	ds_write_b32 v38, v37
	ds_write_b32 v40, v69
	ds_write_b32 v42, v86
	ds_write_b32 v44, v87
	ds_write_b32 v46, v88
	ds_write_b32 v48, v89
	ds_write_b32 v50, v90
	ds_write_b32 v52, v91
	ds_write_b32 v70, v92
	ds_write_b32 v72, v93
	ds_write_b32 v74, v94
	ds_write_b32 v76, v95
	ds_write_b32 v78, v6
	ds_write_b32 v80, v96
	ds_write_b32 v82, v97
	ds_write_b32 v84, v98
	s_waitcnt vmcnt(0)
	ds_write_b32 v138, v137
	ds_write_b32 v140, v169
	ds_write_b32 v142, v186
	ds_write_b32 v144, v187
	ds_write_b32 v146, v188
	ds_write_b32 v148, v189
	ds_write_b32 v150, v190
	ds_write_b32 v152, v191
	ds_write_b32 v170, v192
	ds_write_b32 v172, v193
	ds_write_b32 v174, v194
	ds_write_b32 v176, v195
	ds_write_b32 v178, v106
	ds_write_b32 v180, v196
	ds_write_b32 v182, v197
	ds_write_b32 v184, v198
	s_waitcnt lgkmcnt(0)
	ds_read_b32 v5, v55
	ds_read_b32 v6, v55 offset:132
	ds_read_b32 v35, v55 offset:264
	ds_read_b32 v36, v55 offset:396
	ds_read_b32 v37, v55 offset:528
	ds_read_b32 v40, v55 offset:660
	ds_read_b32 v41, v55 offset:792
	ds_read_b32 v42, v55 offset:924
	s_waitcnt lgkmcnt(0)
	v_bfe_u32 v34, v5, 16, 1
	v_add3_u32 v5, v5, v34, s62
	v_bfe_u32 v34, v6, 16, 1
	v_lshrrev_b32_e32 v5, 16, v5
	v_add3_u32 v6, v6, v34, s62
	v_and_or_b32 v34, v6, s63, v5
	v_bfe_u32 v5, v35, 16, 1
	v_add3_u32 v5, v35, v5, s62
	v_bfe_u32 v6, v36, 16, 1
	v_lshrrev_b32_e32 v5, 16, v5
	v_add3_u32 v6, v36, v6, s62
	v_and_or_b32 v35, v6, s63, v5
	v_bfe_u32 v5, v37, 16, 1
	v_add3_u32 v5, v37, v5, s62
	v_bfe_u32 v6, v40, 16, 1
	v_lshrrev_b32_e32 v5, 16, v5
	v_add3_u32 v6, v40, v6, s62
	v_and_or_b32 v36, v6, s63, v5
	v_bfe_u32 v5, v41, 16, 1
	v_add3_u32 v5, v41, v5, s62
	v_bfe_u32 v6, v42, 16, 1
	v_lshrrev_b32_e32 v5, 16, v5
	v_add3_u32 v6, v42, v6, s62
	s_lshl_b32 s16, s5, 1
	v_and_or_b32 v37, v6, s63, v5
	v_or_b32_e32 v5, s4, v33
	v_lshl_add_u64 v[38:39], v[12:13], 0, s[16:17]
	v_lshlrev_b32_e32 v6, 12, v5
	v_lshl_add_u64 v[40:41], v[38:39], 0, v[6:7]
	flat_store_dwordx4 v[40:41], v[34:37]
	ds_read_b32 v5, v55 offset:32
	ds_read_b32 v6, v55 offset:164
	ds_read_b32 v35, v55 offset:296
	ds_read_b32 v36, v55 offset:428
	ds_read_b32 v37, v55 offset:560
	ds_read_b32 v40, v55 offset:692
	ds_read_b32 v41, v55 offset:824
	ds_read_b32 v42, v55 offset:956
	s_waitcnt lgkmcnt(0)
	v_bfe_u32 v34, v5, 16, 1
	v_add3_u32 v5, v5, v34, s62
	v_bfe_u32 v34, v6, 16, 1
	v_lshrrev_b32_e32 v5, 16, v5
	v_add3_u32 v6, v6, v34, s62
	v_and_or_b32 v34, v6, s63, v5
	v_bfe_u32 v5, v35, 16, 1
	v_add3_u32 v5, v35, v5, s62
	v_bfe_u32 v6, v36, 16, 1
	v_lshrrev_b32_e32 v5, 16, v5
	v_add3_u32 v6, v36, v6, s62
	v_and_or_b32 v35, v6, s63, v5
	v_bfe_u32 v5, v37, 16, 1
	v_add3_u32 v5, v37, v5, s62
	v_bfe_u32 v6, v40, 16, 1
	v_lshrrev_b32_e32 v5, 16, v5
	v_add3_u32 v6, v40, v6, s62
	v_and_or_b32 v36, v6, s63, v5
	v_bfe_u32 v5, v41, 16, 1
	v_add3_u32 v5, v41, v5, s62
	v_bfe_u32 v6, v42, 16, 1
	v_lshrrev_b32_e32 v5, 16, v5
	v_add3_u32 v6, v42, v6, s62
	v_and_or_b32 v37, v6, s63, v5
	v_or_b32_e32 v5, s4, v56
	v_lshlrev_b32_e32 v6, 12, v5
	v_lshl_add_u64 v[40:41], v[38:39], 0, v[6:7]
	flat_store_dwordx4 v[40:41], v[34:37]
	ds_read_b32 v5, v55 offset:64
	ds_read_b32 v6, v55 offset:196
	ds_read_b32 v35, v55 offset:328
	ds_read_b32 v36, v55 offset:460
	ds_read_b32 v37, v55 offset:592
	ds_read_b32 v40, v55 offset:724
	ds_read_b32 v41, v55 offset:856
	ds_read_b32 v42, v55 offset:988
	s_waitcnt lgkmcnt(0)
	v_bfe_u32 v34, v5, 16, 1
	v_add3_u32 v5, v5, v34, s62
	v_bfe_u32 v34, v6, 16, 1
	v_lshrrev_b32_e32 v5, 16, v5
	v_add3_u32 v6, v6, v34, s62
	v_and_or_b32 v34, v6, s63, v5
	v_bfe_u32 v5, v35, 16, 1
	v_add3_u32 v5, v35, v5, s62
	v_bfe_u32 v6, v36, 16, 1
	v_lshrrev_b32_e32 v5, 16, v5
	v_add3_u32 v6, v36, v6, s62
	v_and_or_b32 v35, v6, s63, v5
	v_bfe_u32 v5, v37, 16, 1
	v_add3_u32 v5, v37, v5, s62
	v_bfe_u32 v6, v40, 16, 1
	v_lshrrev_b32_e32 v5, 16, v5
	v_add3_u32 v6, v40, v6, s62
	v_and_or_b32 v36, v6, s63, v5
	v_bfe_u32 v5, v41, 16, 1
	v_add3_u32 v5, v41, v5, s62
	v_bfe_u32 v6, v42, 16, 1
	v_lshrrev_b32_e32 v5, 16, v5
	v_add3_u32 v6, v42, v6, s62
	v_and_or_b32 v37, v6, s63, v5
	v_or_b32_e32 v5, s4, v57
	v_lshlrev_b32_e32 v6, 12, v5
	v_lshl_add_u64 v[40:41], v[38:39], 0, v[6:7]
	flat_store_dwordx4 v[40:41], v[34:37]
	ds_read_b32 v5, v55 offset:96
	ds_read_b32 v6, v55 offset:228
	ds_read_b32 v35, v55 offset:360
	ds_read_b32 v36, v55 offset:492
	ds_read_b32 v37, v55 offset:624
	ds_read_b32 v40, v55 offset:756
	ds_read_b32 v41, v55 offset:888
	ds_read_b32 v42, v55 offset:1020
	s_waitcnt lgkmcnt(0)
	v_bfe_u32 v34, v5, 16, 1
	v_add3_u32 v5, v5, v34, s62
	v_bfe_u32 v34, v6, 16, 1
	v_lshrrev_b32_e32 v5, 16, v5
	v_add3_u32 v6, v6, v34, s62
	v_and_or_b32 v34, v6, s63, v5
	v_bfe_u32 v5, v35, 16, 1
	v_add3_u32 v5, v35, v5, s62
	v_bfe_u32 v6, v36, 16, 1
	v_lshrrev_b32_e32 v5, 16, v5
	v_add3_u32 v6, v36, v6, s62
	v_and_or_b32 v35, v6, s63, v5
	v_bfe_u32 v5, v37, 16, 1
	v_add3_u32 v5, v37, v5, s62
	v_bfe_u32 v6, v40, 16, 1
	v_lshrrev_b32_e32 v5, 16, v5
	v_add3_u32 v6, v40, v6, s62
	v_and_or_b32 v36, v6, s63, v5
	v_bfe_u32 v5, v41, 16, 1
	v_add3_u32 v5, v41, v5, s62
	v_bfe_u32 v6, v42, 16, 1
	v_lshrrev_b32_e32 v5, 16, v5
	v_add3_u32 v6, v42, v6, s62
	v_and_or_b32 v37, v6, s63, v5
	v_or_b32_e32 v5, s4, v58
	v_lshlrev_b32_e32 v6, 12, v5
	v_lshl_add_u64 v[38:39], v[38:39], 0, v[6:7]
	flat_store_dwordx4 v[38:39], v[34:37]
	s_waitcnt lgkmcnt(0)

.LBB0_49:
	s_lshl_b32 s56, s16, 1
	s_lshl_b32 s57, s18, 1
	v_or_b32_e32 v6, s57, v36
	s_add_i32 s58, s56, 4
	s_add_i32 s59, s57, 4
	v_mov_b32_e32 v41, v7
	s_add_i32 s70, s57, 8
	v_lshlrev_b64 v[70:71], 13, v[6:7]
	v_or_b32_e32 v40, s58, v5
	v_or_b32_e32 v6, s59, v36
	v_mov_b32_e32 v39, v7
	v_or_b32_e32 v38, s56, v5
	s_add_i32 s72, s57, 12
	v_lshlrev_b64 v[40:41], 13, v[40:41]
	v_lshlrev_b64 v[72:73], 13, v[6:7]
	v_or_b32_e32 v6, s70, v36
	s_add_i32 s69, s56, 8
	s_add_i32 s71, s56, 12
	s_add_i32 s74, s57, 16
	v_lshlrev_b64 v[38:39], 13, v[38:39]
	v_lshl_add_u64 v[70:71], v[34:35], 0, v[70:71]
	v_lshl_add_u64 v[40:41], v[34:35], 0, v[40:41]
	v_lshlrev_b64 v[74:75], 13, v[6:7]
	v_or_b32_e32 v6, s72, v36
	v_mov_b32_e32 v43, v7
	v_mov_b32_e32 v45, v7
	s_add_i32 s76, s57, 20
	v_or_b32_e32 v42, s69, v5
	v_or_b32_e32 v44, s71, v5
	v_lshl_add_u64 v[38:39], v[34:35], 0, v[38:39]
	v_lshl_add_u64 v[72:73], v[34:35], 0, v[72:73]
	global_load_dword v37, v[70:71], off
	global_load_dword v69, v[38:39], off
	global_load_dword v86, v[72:73], off
	global_load_dword v87, v[40:41], off
	v_lshlrev_b64 v[40:41], 13, v[6:7]
	v_or_b32_e32 v6, s74, v36
	s_add_i32 s73, s56, 16
	s_add_i32 s75, s56, 20
	s_add_i32 s78, s57, 24
	v_lshlrev_b64 v[42:43], 13, v[42:43]
	v_lshlrev_b64 v[44:45], 13, v[44:45]
	v_lshl_add_u64 v[38:39], v[34:35], 0, v[74:75]
	v_lshl_add_u64 v[40:41], v[34:35], 0, v[40:41]
	v_lshlrev_b64 v[70:71], 13, v[6:7]
	v_or_b32_e32 v6, s76, v36
	v_mov_b32_e32 v47, v7
	v_mov_b32_e32 v49, v7
	s_add_i32 s77, s56, 24
	s_add_i32 s79, s56, 28
	s_add_i32 s80, s57, 28
	v_or_b32_e32 v46, s73, v5
	v_or_b32_e32 v48, s75, v5
	v_lshl_add_u64 v[42:43], v[34:35], 0, v[42:43]
	v_lshl_add_u64 v[44:45], v[34:35], 0, v[44:45]
	global_load_dword v88, v[38:39], off
	global_load_dword v89, v[42:43], off
	global_load_dword v90, v[40:41], off
	global_load_dword v91, v[44:45], off
	v_lshlrev_b64 v[40:41], 13, v[6:7]
	v_or_b32_e32 v6, s78, v36
	v_mov_b32_e32 v51, v7
	v_mov_b32_e32 v53, v7
	v_or_b32_e32 v50, s77, v5
	v_or_b32_e32 v52, s79, v5
	v_lshlrev_b64 v[46:47], 13, v[46:47]
	v_lshlrev_b64 v[48:49], 13, v[48:49]
	v_lshl_add_u64 v[38:39], v[34:35], 0, v[70:71]
	v_lshl_add_u64 v[40:41], v[34:35], 0, v[40:41]
	v_lshlrev_b64 v[42:43], 13, v[6:7]
	v_or_b32_e32 v6, s80, v36
	v_lshlrev_b64 v[50:51], 13, v[50:51]
	v_lshlrev_b64 v[52:53], 13, v[52:53]
	v_lshl_add_u64 v[46:47], v[34:35], 0, v[46:47]
	v_lshl_add_u64 v[48:49], v[34:35], 0, v[48:49]
	global_load_dword v92, v[38:39], off
	global_load_dword v93, v[46:47], off
	global_load_dword v94, v[40:41], off
	global_load_dword v95, v[48:49], off
	v_lshl_add_u64 v[38:39], v[34:35], 0, v[42:43]
	v_lshlrev_b64 v[40:41], 13, v[6:7]
	v_lshl_add_u64 v[50:51], v[34:35], 0, v[50:51]
	v_lshl_add_u64 v[52:53], v[34:35], 0, v[52:53]
	v_lshl_add_u64 v[40:41], v[34:35], 0, v[40:41]
	global_load_dword v6, v[38:39], off
	global_load_dword v96, v[50:51], off
	global_load_dword v97, v[40:41], off
	global_load_dword v98, v[52:53], off
	v_or_b32_e32 v40, s56, v1
	v_or_b32_e32 v38, s57, v2
	s_add_i32 s18, s18, 16
	s_add_i32 s16, s16, 16
	s_add_i32 s19, s19, -16
	v_mad_u64_u32 v[38:39], s[56:57], v38, s13, v[4:5]
	v_mad_u64_u32 v[40:41], s[56:57], v40, s13, v[4:5]
	v_or_b32_e32 v39, s58, v1
	v_or_b32_e32 v41, s59, v2
	v_or_b32_e32 v48, s69, v1
	v_or_b32_e32 v46, s70, v2
	v_or_b32_e32 v52, s71, v1
	v_or_b32_e32 v50, s72, v2
	v_or_b32_e32 v72, s73, v1
	v_or_b32_e32 v70, s74, v2
	v_or_b32_e32 v76, s75, v1
	v_or_b32_e32 v74, s76, v2
	v_or_b32_e32 v80, s77, v1
	v_or_b32_e32 v78, s78, v2
	v_or_b32_e32 v84, s79, v1
	v_or_b32_e32 v82, s80, v2
	s_cmp_lg_u32 s19, 0
	v_mad_u64_u32 v[42:43], s[56:57], v41, s13, v[4:5]
	v_mad_u64_u32 v[44:45], s[56:57], v39, s13, v[4:5]
	v_mad_u64_u32 v[46:47], s[56:57], v46, s13, v[4:5]
	v_mad_u64_u32 v[48:49], s[56:57], v48, s13, v[4:5]
	v_mad_u64_u32 v[50:51], s[56:57], v50, s13, v[4:5]
	v_mad_u64_u32 v[52:53], s[56:57], v52, s13, v[4:5]
	v_mad_u64_u32 v[70:71], s[56:57], v70, s13, v[4:5]
	v_mad_u64_u32 v[72:73], s[56:57], v72, s13, v[4:5]
	v_mad_u64_u32 v[74:75], s[56:57], v74, s13, v[4:5]
	v_mad_u64_u32 v[76:77], s[56:57], v76, s13, v[4:5]
	v_mad_u64_u32 v[78:79], s[56:57], v78, s13, v[4:5]
	v_mad_u64_u32 v[80:81], s[56:57], v80, s13, v[4:5]
	v_mad_u64_u32 v[82:83], s[56:57], v82, s13, v[4:5]
	v_mad_u64_u32 v[84:85], s[56:57], v84, s13, v[4:5]
	v_mov_b32_e32 v107, v7
	s_lshl_b32 s56, s16, 1
	s_lshl_b32 s57, s18, 1
	v_or_b32_e32 v106, s57, v36
	s_add_i32 s58, s56, 4
	s_add_i32 s59, s57, 4
	v_mov_b32_e32 v141, v107
	s_add_i32 s70, s57, 8
	v_lshlrev_b64 v[170:171], 13, v[106:107]
	v_or_b32_e32 v140, s58, v5
	v_or_b32_e32 v106, s59, v36
	v_mov_b32_e32 v139, v107
	v_or_b32_e32 v138, s56, v5
	s_add_i32 s72, s57, 12
	v_lshlrev_b64 v[140:141], 13, v[140:141]
	v_lshlrev_b64 v[172:173], 13, v[106:107]
	v_or_b32_e32 v106, s70, v36
	s_add_i32 s69, s56, 8
	s_add_i32 s71, s56, 12
	s_add_i32 s74, s57, 16
	v_lshlrev_b64 v[138:139], 13, v[138:139]
	v_lshl_add_u64 v[170:171], v[34:35], 0, v[170:171]
	v_lshl_add_u64 v[140:141], v[34:35], 0, v[140:141]
	v_lshlrev_b64 v[174:175], 13, v[106:107]
	v_or_b32_e32 v106, s72, v36
	v_mov_b32_e32 v143, v107
	v_mov_b32_e32 v145, v107
	s_add_i32 s76, s57, 20
	v_or_b32_e32 v142, s69, v5
	v_or_b32_e32 v144, s71, v5
	v_lshl_add_u64 v[138:139], v[34:35], 0, v[138:139]
	v_lshl_add_u64 v[172:173], v[34:35], 0, v[172:173]
	global_load_dword v137, v[170:171], off
	global_load_dword v169, v[138:139], off
	global_load_dword v186, v[172:173], off
	global_load_dword v187, v[140:141], off
	v_lshlrev_b64 v[140:141], 13, v[106:107]
	v_or_b32_e32 v106, s74, v36
	s_add_i32 s73, s56, 16
	s_add_i32 s75, s56, 20
	s_add_i32 s78, s57, 24
	v_lshlrev_b64 v[142:143], 13, v[142:143]
	v_lshlrev_b64 v[144:145], 13, v[144:145]
	v_lshl_add_u64 v[138:139], v[34:35], 0, v[174:175]
	v_lshl_add_u64 v[140:141], v[34:35], 0, v[140:141]
	v_lshlrev_b64 v[170:171], 13, v[106:107]
	v_or_b32_e32 v106, s76, v36
	v_mov_b32_e32 v147, v107
	v_mov_b32_e32 v149, v107
	s_add_i32 s77, s56, 24
	s_add_i32 s79, s56, 28
	s_add_i32 s80, s57, 28
	v_or_b32_e32 v146, s73, v5
	v_or_b32_e32 v148, s75, v5
	v_lshl_add_u64 v[142:143], v[34:35], 0, v[142:143]
	v_lshl_add_u64 v[144:145], v[34:35], 0, v[144:145]
	global_load_dword v188, v[138:139], off
	global_load_dword v189, v[142:143], off
	global_load_dword v190, v[140:141], off
	global_load_dword v191, v[144:145], off
	v_lshlrev_b64 v[140:141], 13, v[106:107]
	v_or_b32_e32 v106, s78, v36
	v_mov_b32_e32 v151, v107
	v_mov_b32_e32 v153, v107
	v_or_b32_e32 v150, s77, v5
	v_or_b32_e32 v152, s79, v5
	v_lshlrev_b64 v[146:147], 13, v[146:147]
	v_lshlrev_b64 v[148:149], 13, v[148:149]
	v_lshl_add_u64 v[138:139], v[34:35], 0, v[170:171]
	v_lshl_add_u64 v[140:141], v[34:35], 0, v[140:141]
	v_lshlrev_b64 v[142:143], 13, v[106:107]
	v_or_b32_e32 v106, s80, v36
	v_lshlrev_b64 v[150:151], 13, v[150:151]
	v_lshlrev_b64 v[152:153], 13, v[152:153]
	v_lshl_add_u64 v[146:147], v[34:35], 0, v[146:147]
	v_lshl_add_u64 v[148:149], v[34:35], 0, v[148:149]
	global_load_dword v192, v[138:139], off
	global_load_dword v193, v[146:147], off
	global_load_dword v194, v[140:141], off
	global_load_dword v195, v[148:149], off
	v_lshl_add_u64 v[138:139], v[34:35], 0, v[142:143]
	v_lshlrev_b64 v[140:141], 13, v[106:107]
	v_lshl_add_u64 v[150:151], v[34:35], 0, v[150:151]
	v_lshl_add_u64 v[152:153], v[34:35], 0, v[152:153]
	v_lshl_add_u64 v[140:141], v[34:35], 0, v[140:141]
	global_load_dword v106, v[138:139], off
	global_load_dword v196, v[150:151], off
	global_load_dword v197, v[140:141], off
	global_load_dword v198, v[152:153], off
	v_or_b32_e32 v140, s56, v1
	v_or_b32_e32 v138, s57, v2
	s_add_i32 s18, s18, 16
	s_add_i32 s16, s16, 16
	s_add_i32 s19, s19, -16
	v_mad_u64_u32 v[138:139], s[56:57], v138, s13, v[4:5]
	v_mad_u64_u32 v[140:141], s[56:57], v140, s13, v[4:5]
	v_or_b32_e32 v139, s58, v1
	v_or_b32_e32 v141, s59, v2
	v_or_b32_e32 v148, s69, v1
	v_or_b32_e32 v146, s70, v2
	v_or_b32_e32 v152, s71, v1
	v_or_b32_e32 v150, s72, v2
	v_or_b32_e32 v172, s73, v1
	v_or_b32_e32 v170, s74, v2
	v_or_b32_e32 v176, s75, v1
	v_or_b32_e32 v174, s76, v2
	v_or_b32_e32 v180, s77, v1
	v_or_b32_e32 v178, s78, v2
	v_or_b32_e32 v184, s79, v1
	v_or_b32_e32 v182, s80, v2
	s_cmp_lg_u32 s19, 0
	v_mad_u64_u32 v[142:143], s[56:57], v141, s13, v[4:5]
	v_mad_u64_u32 v[144:145], s[56:57], v139, s13, v[4:5]
	v_mad_u64_u32 v[146:147], s[56:57], v146, s13, v[4:5]
	v_mad_u64_u32 v[148:149], s[56:57], v148, s13, v[4:5]
	v_mad_u64_u32 v[150:151], s[56:57], v150, s13, v[4:5]
	v_mad_u64_u32 v[152:153], s[56:57], v152, s13, v[4:5]
	v_mad_u64_u32 v[170:171], s[56:57], v170, s13, v[4:5]
	v_mad_u64_u32 v[172:173], s[56:57], v172, s13, v[4:5]
	v_mad_u64_u32 v[174:175], s[56:57], v174, s13, v[4:5]
	v_mad_u64_u32 v[176:177], s[56:57], v176, s13, v[4:5]
	v_mad_u64_u32 v[178:179], s[56:57], v178, s13, v[4:5]
	v_mad_u64_u32 v[180:181], s[56:57], v180, s13, v[4:5]
	v_mad_u64_u32 v[182:183], s[56:57], v182, s13, v[4:5]
	v_mad_u64_u32 v[184:185], s[56:57], v184, s13, v[4:5]
	s_waitcnt vmcnt(16)
	ds_write_b32 v38, v37
	ds_write_b32 v40, v69
	ds_write_b32 v42, v86
	ds_write_b32 v44, v87
	ds_write_b32 v46, v88
	ds_write_b32 v48, v89
	ds_write_b32 v50, v90
	ds_write_b32 v52, v91
	ds_write_b32 v70, v92
	ds_write_b32 v72, v93
	ds_write_b32 v74, v94
	ds_write_b32 v76, v95
	ds_write_b32 v78, v6
	ds_write_b32 v80, v96
	ds_write_b32 v82, v97
	ds_write_b32 v84, v98
	s_waitcnt vmcnt(0)
	ds_write_b32 v138, v137
	ds_write_b32 v140, v169
	ds_write_b32 v142, v186
	ds_write_b32 v144, v187
	ds_write_b32 v146, v188
	ds_write_b32 v148, v189
	ds_write_b32 v150, v190
	ds_write_b32 v152, v191
	ds_write_b32 v170, v192
	ds_write_b32 v172, v193
	ds_write_b32 v174, v194
	ds_write_b32 v176, v195
	ds_write_b32 v178, v106
	ds_write_b32 v180, v196
	ds_write_b32 v182, v197
	ds_write_b32 v184, v198
	s_waitcnt lgkmcnt(0)
	ds_read_b32 v5, v55
	ds_read_b32 v6, v55 offset:132
	ds_read_b32 v35, v55 offset:264
	ds_read_b32 v36, v55 offset:396
	ds_read_b32 v37, v55 offset:528
	ds_read_b32 v40, v55 offset:660
	ds_read_b32 v41, v55 offset:792
	ds_read_b32 v42, v55 offset:924
	s_waitcnt lgkmcnt(0)
	v_bfe_u32 v34, v5, 16, 1
	v_add3_u32 v5, v5, v34, s62
	v_bfe_u32 v34, v6, 16, 1
	v_lshrrev_b32_e32 v5, 16, v5
	v_add3_u32 v6, v6, v34, s62
	v_and_or_b32 v34, v6, s63, v5
	v_bfe_u32 v5, v35, 16, 1
	v_add3_u32 v5, v35, v5, s62
	v_bfe_u32 v6, v36, 16, 1
	v_lshrrev_b32_e32 v5, 16, v5
	v_add3_u32 v6, v36, v6, s62
	v_and_or_b32 v35, v6, s63, v5
	v_bfe_u32 v5, v37, 16, 1
	v_add3_u32 v5, v37, v5, s62
	v_bfe_u32 v6, v40, 16, 1
	v_lshrrev_b32_e32 v5, 16, v5
	v_add3_u32 v6, v40, v6, s62
	v_and_or_b32 v36, v6, s63, v5
	v_bfe_u32 v5, v41, 16, 1
	v_add3_u32 v5, v41, v5, s62
	v_bfe_u32 v6, v42, 16, 1
	v_lshrrev_b32_e32 v5, 16, v5
	v_add3_u32 v6, v42, v6, s62
	v_and_or_b32 v37, v6, s63, v5
	v_or_b32_e32 v5, s4, v33
	s_lshl_b32 s16, s5, 1
	v_mul_u32_u24_e32 v5, 0xc00, v5
	v_lshl_add_u64 v[38:39], v[14:15], 0, s[16:17]
	v_lshlrev_b32_e32 v6, 1, v5
	v_lshl_add_u64 v[40:41], v[38:39], 0, v[6:7]
	flat_store_dwordx4 v[40:41], v[34:37]
	ds_read_b32 v5, v55 offset:32
	ds_read_b32 v6, v55 offset:164
	ds_read_b32 v35, v55 offset:296
	ds_read_b32 v36, v55 offset:428
	ds_read_b32 v37, v55 offset:560
	ds_read_b32 v40, v55 offset:692
	ds_read_b32 v41, v55 offset:824
	ds_read_b32 v42, v55 offset:956
	s_waitcnt lgkmcnt(0)
	v_bfe_u32 v34, v5, 16, 1
	v_add3_u32 v5, v5, v34, s62
	v_bfe_u32 v34, v6, 16, 1
	v_lshrrev_b32_e32 v5, 16, v5
	v_add3_u32 v6, v6, v34, s62
	v_and_or_b32 v34, v6, s63, v5
	v_bfe_u32 v5, v35, 16, 1
	v_add3_u32 v5, v35, v5, s62
	v_bfe_u32 v6, v36, 16, 1
	v_lshrrev_b32_e32 v5, 16, v5
	v_add3_u32 v6, v36, v6, s62
	v_and_or_b32 v35, v6, s63, v5
	v_bfe_u32 v5, v37, 16, 1
	v_add3_u32 v5, v37, v5, s62
	v_bfe_u32 v6, v40, 16, 1
	v_lshrrev_b32_e32 v5, 16, v5
	v_add3_u32 v6, v40, v6, s62
	v_and_or_b32 v36, v6, s63, v5
	v_bfe_u32 v5, v41, 16, 1
	v_add3_u32 v5, v41, v5, s62
	v_bfe_u32 v6, v42, 16, 1
	v_lshrrev_b32_e32 v5, 16, v5
	v_add3_u32 v6, v42, v6, s62
	v_and_or_b32 v37, v6, s63, v5
	v_or_b32_e32 v5, s4, v56
	v_mul_u32_u24_e32 v5, 0xc00, v5
	v_lshlrev_b32_e32 v6, 1, v5
	v_lshl_add_u64 v[40:41], v[38:39], 0, v[6:7]
	flat_store_dwordx4 v[40:41], v[34:37]
	ds_read_b32 v5, v55 offset:64
	ds_read_b32 v6, v55 offset:196
	ds_read_b32 v35, v55 offset:328
	ds_read_b32 v36, v55 offset:460
	ds_read_b32 v37, v55 offset:592
	ds_read_b32 v40, v55 offset:724
	ds_read_b32 v41, v55 offset:856
	ds_read_b32 v42, v55 offset:988
	s_waitcnt lgkmcnt(0)
	v_bfe_u32 v34, v5, 16, 1
	v_add3_u32 v5, v5, v34, s62
	v_bfe_u32 v34, v6, 16, 1
	v_lshrrev_b32_e32 v5, 16, v5
	v_add3_u32 v6, v6, v34, s62
	v_and_or_b32 v34, v6, s63, v5
	v_bfe_u32 v5, v35, 16, 1
	v_add3_u32 v5, v35, v5, s62
	v_bfe_u32 v6, v36, 16, 1
	v_lshrrev_b32_e32 v5, 16, v5
	v_add3_u32 v6, v36, v6, s62
	v_and_or_b32 v35, v6, s63, v5
	v_bfe_u32 v5, v37, 16, 1
	v_add3_u32 v5, v37, v5, s62
	v_bfe_u32 v6, v40, 16, 1
	v_lshrrev_b32_e32 v5, 16, v5
	v_add3_u32 v6, v40, v6, s62
	v_and_or_b32 v36, v6, s63, v5
	v_bfe_u32 v5, v41, 16, 1
	v_add3_u32 v5, v41, v5, s62
	v_bfe_u32 v6, v42, 16, 1
	v_lshrrev_b32_e32 v5, 16, v5
	v_add3_u32 v6, v42, v6, s62
	v_and_or_b32 v37, v6, s63, v5
	v_or_b32_e32 v5, s4, v57
	v_mul_u32_u24_e32 v5, 0xc00, v5
	v_lshlrev_b32_e32 v6, 1, v5
	v_lshl_add_u64 v[40:41], v[38:39], 0, v[6:7]
	flat_store_dwordx4 v[40:41], v[34:37]
	ds_read_b32 v5, v55 offset:96
	ds_read_b32 v6, v55 offset:228
	ds_read_b32 v35, v55 offset:360
	ds_read_b32 v36, v55 offset:492
	ds_read_b32 v37, v55 offset:624
	ds_read_b32 v40, v55 offset:756
	ds_read_b32 v41, v55 offset:888
	ds_read_b32 v42, v55 offset:1020
	s_waitcnt lgkmcnt(0)
	v_bfe_u32 v34, v5, 16, 1
	v_add3_u32 v5, v5, v34, s62
	v_bfe_u32 v34, v6, 16, 1
	v_lshrrev_b32_e32 v5, 16, v5
	v_add3_u32 v6, v6, v34, s62
	v_and_or_b32 v34, v6, s63, v5
	v_bfe_u32 v5, v35, 16, 1
	v_add3_u32 v5, v35, v5, s62
	v_bfe_u32 v6, v36, 16, 1
	v_lshrrev_b32_e32 v5, 16, v5
	v_add3_u32 v6, v36, v6, s62
	v_and_or_b32 v35, v6, s63, v5
	v_bfe_u32 v5, v37, 16, 1
	v_add3_u32 v5, v37, v5, s62
	v_bfe_u32 v6, v40, 16, 1
	v_lshrrev_b32_e32 v5, 16, v5
	v_add3_u32 v6, v40, v6, s62
	v_and_or_b32 v36, v6, s63, v5
	v_bfe_u32 v5, v41, 16, 1
	v_add3_u32 v5, v41, v5, s62
	v_bfe_u32 v6, v42, 16, 1
	v_lshrrev_b32_e32 v5, 16, v5
	v_add3_u32 v6, v42, v6, s62
	v_and_or_b32 v37, v6, s63, v5
	v_or_b32_e32 v5, s4, v58
	v_mul_u32_u24_e32 v5, 0xc00, v5
	v_lshlrev_b32_e32 v6, 1, v5
	v_lshl_add_u64 v[38:39], v[38:39], 0, v[6:7]
	flat_store_dwordx4 v[38:39], v[34:37]
	s_waitcnt lgkmcnt(0)

.LBB0_54:
	s_lshl_b32 s56, s16, 1
	s_lshl_b32 s57, s18, 1
	v_or_b32_e32 v6, s57, v36
	s_add_i32 s58, s56, 4
	s_add_i32 s59, s57, 4
	v_mov_b32_e32 v41, v7
	s_add_i32 s70, s57, 8
	v_lshlrev_b64 v[70:71], 13, v[6:7]
	v_or_b32_e32 v40, s58, v5
	v_or_b32_e32 v6, s59, v36
	v_mov_b32_e32 v39, v7
	v_or_b32_e32 v38, s56, v5
	s_add_i32 s72, s57, 12
	v_lshlrev_b64 v[40:41], 13, v[40:41]
	v_lshlrev_b64 v[72:73], 13, v[6:7]
	v_or_b32_e32 v6, s70, v36
	s_add_i32 s69, s56, 8
	s_add_i32 s71, s56, 12
	s_add_i32 s74, s57, 16
	v_lshlrev_b64 v[38:39], 13, v[38:39]
	v_lshl_add_u64 v[70:71], v[34:35], 0, v[70:71]
	v_lshl_add_u64 v[40:41], v[34:35], 0, v[40:41]
	v_lshlrev_b64 v[74:75], 13, v[6:7]
	v_or_b32_e32 v6, s72, v36
	v_mov_b32_e32 v43, v7
	v_mov_b32_e32 v45, v7
	s_add_i32 s76, s57, 20
	v_or_b32_e32 v42, s69, v5
	v_or_b32_e32 v44, s71, v5
	v_lshl_add_u64 v[38:39], v[34:35], 0, v[38:39]
	v_lshl_add_u64 v[72:73], v[34:35], 0, v[72:73]
	global_load_dword v37, v[70:71], off
	global_load_dword v69, v[38:39], off
	global_load_dword v86, v[72:73], off
	global_load_dword v87, v[40:41], off
	v_lshlrev_b64 v[40:41], 13, v[6:7]
	v_or_b32_e32 v6, s74, v36
	s_add_i32 s73, s56, 16
	s_add_i32 s75, s56, 20
	s_add_i32 s78, s57, 24
	v_lshlrev_b64 v[42:43], 13, v[42:43]
	v_lshlrev_b64 v[44:45], 13, v[44:45]
	v_lshl_add_u64 v[38:39], v[34:35], 0, v[74:75]
	v_lshl_add_u64 v[40:41], v[34:35], 0, v[40:41]
	v_lshlrev_b64 v[70:71], 13, v[6:7]
	v_or_b32_e32 v6, s76, v36
	v_mov_b32_e32 v47, v7
	v_mov_b32_e32 v49, v7
	s_add_i32 s77, s56, 24
	s_add_i32 s79, s56, 28
	s_add_i32 s80, s57, 28
	v_or_b32_e32 v46, s73, v5
	v_or_b32_e32 v48, s75, v5
	v_lshl_add_u64 v[42:43], v[34:35], 0, v[42:43]
	v_lshl_add_u64 v[44:45], v[34:35], 0, v[44:45]
	global_load_dword v88, v[38:39], off
	global_load_dword v89, v[42:43], off
	global_load_dword v90, v[40:41], off
	global_load_dword v91, v[44:45], off
	v_lshlrev_b64 v[40:41], 13, v[6:7]
	v_or_b32_e32 v6, s78, v36
	v_mov_b32_e32 v51, v7
	v_mov_b32_e32 v53, v7
	v_or_b32_e32 v50, s77, v5
	v_or_b32_e32 v52, s79, v5
	v_lshlrev_b64 v[46:47], 13, v[46:47]
	v_lshlrev_b64 v[48:49], 13, v[48:49]
	v_lshl_add_u64 v[38:39], v[34:35], 0, v[70:71]
	v_lshl_add_u64 v[40:41], v[34:35], 0, v[40:41]
	v_lshlrev_b64 v[42:43], 13, v[6:7]
	v_or_b32_e32 v6, s80, v36
	v_lshlrev_b64 v[50:51], 13, v[50:51]
	v_lshlrev_b64 v[52:53], 13, v[52:53]
	v_lshl_add_u64 v[46:47], v[34:35], 0, v[46:47]
	v_lshl_add_u64 v[48:49], v[34:35], 0, v[48:49]
	global_load_dword v92, v[38:39], off
	global_load_dword v93, v[46:47], off
	global_load_dword v94, v[40:41], off
	global_load_dword v95, v[48:49], off
	v_lshl_add_u64 v[38:39], v[34:35], 0, v[42:43]
	v_lshlrev_b64 v[40:41], 13, v[6:7]
	v_lshl_add_u64 v[50:51], v[34:35], 0, v[50:51]
	v_lshl_add_u64 v[52:53], v[34:35], 0, v[52:53]
	v_lshl_add_u64 v[40:41], v[34:35], 0, v[40:41]
	global_load_dword v6, v[38:39], off
	global_load_dword v96, v[50:51], off
	global_load_dword v97, v[40:41], off
	global_load_dword v98, v[52:53], off
	v_or_b32_e32 v40, s56, v1
	v_or_b32_e32 v38, s57, v2
	s_add_i32 s18, s18, 16
	s_add_i32 s16, s16, 16
	s_add_i32 s19, s19, -16
	v_mad_u64_u32 v[38:39], s[56:57], v38, s13, v[4:5]
	v_mad_u64_u32 v[40:41], s[56:57], v40, s13, v[4:5]
	v_or_b32_e32 v39, s58, v1
	v_or_b32_e32 v41, s59, v2
	v_or_b32_e32 v48, s69, v1
	v_or_b32_e32 v46, s70, v2
	v_or_b32_e32 v52, s71, v1
	v_or_b32_e32 v50, s72, v2
	v_or_b32_e32 v72, s73, v1
	v_or_b32_e32 v70, s74, v2
	v_or_b32_e32 v76, s75, v1
	v_or_b32_e32 v74, s76, v2
	v_or_b32_e32 v80, s77, v1
	v_or_b32_e32 v78, s78, v2
	v_or_b32_e32 v84, s79, v1
	v_or_b32_e32 v82, s80, v2
	s_cmp_lg_u32 s19, 0
	v_mad_u64_u32 v[42:43], s[56:57], v41, s13, v[4:5]
	v_mad_u64_u32 v[44:45], s[56:57], v39, s13, v[4:5]
	v_mad_u64_u32 v[46:47], s[56:57], v46, s13, v[4:5]
	v_mad_u64_u32 v[48:49], s[56:57], v48, s13, v[4:5]
	v_mad_u64_u32 v[50:51], s[56:57], v50, s13, v[4:5]
	v_mad_u64_u32 v[52:53], s[56:57], v52, s13, v[4:5]
	v_mad_u64_u32 v[70:71], s[56:57], v70, s13, v[4:5]
	v_mad_u64_u32 v[72:73], s[56:57], v72, s13, v[4:5]
	v_mad_u64_u32 v[74:75], s[56:57], v74, s13, v[4:5]
	v_mad_u64_u32 v[76:77], s[56:57], v76, s13, v[4:5]
	v_mad_u64_u32 v[78:79], s[56:57], v78, s13, v[4:5]
	v_mad_u64_u32 v[80:81], s[56:57], v80, s13, v[4:5]
	v_mad_u64_u32 v[82:83], s[56:57], v82, s13, v[4:5]
	v_mad_u64_u32 v[84:85], s[56:57], v84, s13, v[4:5]
	v_mov_b32_e32 v107, v7
	s_lshl_b32 s56, s16, 1
	s_lshl_b32 s57, s18, 1
	v_or_b32_e32 v106, s57, v36
	s_add_i32 s58, s56, 4
	s_add_i32 s59, s57, 4
	v_mov_b32_e32 v141, v107
	s_add_i32 s70, s57, 8
	v_lshlrev_b64 v[170:171], 13, v[106:107]
	v_or_b32_e32 v140, s58, v5
	v_or_b32_e32 v106, s59, v36
	v_mov_b32_e32 v139, v107
	v_or_b32_e32 v138, s56, v5
	s_add_i32 s72, s57, 12
	v_lshlrev_b64 v[140:141], 13, v[140:141]
	v_lshlrev_b64 v[172:173], 13, v[106:107]
	v_or_b32_e32 v106, s70, v36
	s_add_i32 s69, s56, 8
	s_add_i32 s71, s56, 12
	s_add_i32 s74, s57, 16
	v_lshlrev_b64 v[138:139], 13, v[138:139]
	v_lshl_add_u64 v[170:171], v[34:35], 0, v[170:171]
	v_lshl_add_u64 v[140:141], v[34:35], 0, v[140:141]
	v_lshlrev_b64 v[174:175], 13, v[106:107]
	v_or_b32_e32 v106, s72, v36
	v_mov_b32_e32 v143, v107
	v_mov_b32_e32 v145, v107
	s_add_i32 s76, s57, 20
	v_or_b32_e32 v142, s69, v5
	v_or_b32_e32 v144, s71, v5
	v_lshl_add_u64 v[138:139], v[34:35], 0, v[138:139]
	v_lshl_add_u64 v[172:173], v[34:35], 0, v[172:173]
	global_load_dword v137, v[170:171], off
	global_load_dword v169, v[138:139], off
	global_load_dword v186, v[172:173], off
	global_load_dword v187, v[140:141], off
	v_lshlrev_b64 v[140:141], 13, v[106:107]
	v_or_b32_e32 v106, s74, v36
	s_add_i32 s73, s56, 16
	s_add_i32 s75, s56, 20
	s_add_i32 s78, s57, 24
	v_lshlrev_b64 v[142:143], 13, v[142:143]
	v_lshlrev_b64 v[144:145], 13, v[144:145]
	v_lshl_add_u64 v[138:139], v[34:35], 0, v[174:175]
	v_lshl_add_u64 v[140:141], v[34:35], 0, v[140:141]
	v_lshlrev_b64 v[170:171], 13, v[106:107]
	v_or_b32_e32 v106, s76, v36
	v_mov_b32_e32 v147, v107
	v_mov_b32_e32 v149, v107
	s_add_i32 s77, s56, 24
	s_add_i32 s79, s56, 28
	s_add_i32 s80, s57, 28
	v_or_b32_e32 v146, s73, v5
	v_or_b32_e32 v148, s75, v5
	v_lshl_add_u64 v[142:143], v[34:35], 0, v[142:143]
	v_lshl_add_u64 v[144:145], v[34:35], 0, v[144:145]
	global_load_dword v188, v[138:139], off
	global_load_dword v189, v[142:143], off
	global_load_dword v190, v[140:141], off
	global_load_dword v191, v[144:145], off
	v_lshlrev_b64 v[140:141], 13, v[106:107]
	v_or_b32_e32 v106, s78, v36
	v_mov_b32_e32 v151, v107
	v_mov_b32_e32 v153, v107
	v_or_b32_e32 v150, s77, v5
	v_or_b32_e32 v152, s79, v5
	v_lshlrev_b64 v[146:147], 13, v[146:147]
	v_lshlrev_b64 v[148:149], 13, v[148:149]
	v_lshl_add_u64 v[138:139], v[34:35], 0, v[170:171]
	v_lshl_add_u64 v[140:141], v[34:35], 0, v[140:141]
	v_lshlrev_b64 v[142:143], 13, v[106:107]
	v_or_b32_e32 v106, s80, v36
	v_lshlrev_b64 v[150:151], 13, v[150:151]
	v_lshlrev_b64 v[152:153], 13, v[152:153]
	v_lshl_add_u64 v[146:147], v[34:35], 0, v[146:147]
	v_lshl_add_u64 v[148:149], v[34:35], 0, v[148:149]
	global_load_dword v192, v[138:139], off
	global_load_dword v193, v[146:147], off
	global_load_dword v194, v[140:141], off
	global_load_dword v195, v[148:149], off
	v_lshl_add_u64 v[138:139], v[34:35], 0, v[142:143]
	v_lshlrev_b64 v[140:141], 13, v[106:107]
	v_lshl_add_u64 v[150:151], v[34:35], 0, v[150:151]
	v_lshl_add_u64 v[152:153], v[34:35], 0, v[152:153]
	v_lshl_add_u64 v[140:141], v[34:35], 0, v[140:141]
	global_load_dword v106, v[138:139], off
	global_load_dword v196, v[150:151], off
	global_load_dword v197, v[140:141], off
	global_load_dword v198, v[152:153], off
	v_or_b32_e32 v140, s56, v1
	v_or_b32_e32 v138, s57, v2
	s_add_i32 s18, s18, 16
	s_add_i32 s16, s16, 16
	s_add_i32 s19, s19, -16
	v_mad_u64_u32 v[138:139], s[56:57], v138, s13, v[4:5]
	v_mad_u64_u32 v[140:141], s[56:57], v140, s13, v[4:5]
	v_or_b32_e32 v139, s58, v1
	v_or_b32_e32 v141, s59, v2
	v_or_b32_e32 v148, s69, v1
	v_or_b32_e32 v146, s70, v2
	v_or_b32_e32 v152, s71, v1
	v_or_b32_e32 v150, s72, v2
	v_or_b32_e32 v172, s73, v1
	v_or_b32_e32 v170, s74, v2
	v_or_b32_e32 v176, s75, v1
	v_or_b32_e32 v174, s76, v2
	v_or_b32_e32 v180, s77, v1
	v_or_b32_e32 v178, s78, v2
	v_or_b32_e32 v184, s79, v1
	v_or_b32_e32 v182, s80, v2
	s_cmp_lg_u32 s19, 0
	v_mad_u64_u32 v[142:143], s[56:57], v141, s13, v[4:5]
	v_mad_u64_u32 v[144:145], s[56:57], v139, s13, v[4:5]
	v_mad_u64_u32 v[146:147], s[56:57], v146, s13, v[4:5]
	v_mad_u64_u32 v[148:149], s[56:57], v148, s13, v[4:5]
	v_mad_u64_u32 v[150:151], s[56:57], v150, s13, v[4:5]
	v_mad_u64_u32 v[152:153], s[56:57], v152, s13, v[4:5]
	v_mad_u64_u32 v[170:171], s[56:57], v170, s13, v[4:5]
	v_mad_u64_u32 v[172:173], s[56:57], v172, s13, v[4:5]
	v_mad_u64_u32 v[174:175], s[56:57], v174, s13, v[4:5]
	v_mad_u64_u32 v[176:177], s[56:57], v176, s13, v[4:5]
	v_mad_u64_u32 v[178:179], s[56:57], v178, s13, v[4:5]
	v_mad_u64_u32 v[180:181], s[56:57], v180, s13, v[4:5]
	v_mad_u64_u32 v[182:183], s[56:57], v182, s13, v[4:5]
	v_mad_u64_u32 v[184:185], s[56:57], v184, s13, v[4:5]
	s_waitcnt vmcnt(16)
	ds_write_b32 v38, v37
	ds_write_b32 v40, v69
	ds_write_b32 v42, v86
	ds_write_b32 v44, v87
	ds_write_b32 v46, v88
	ds_write_b32 v48, v89
	ds_write_b32 v50, v90
	ds_write_b32 v52, v91
	ds_write_b32 v70, v92
	ds_write_b32 v72, v93
	ds_write_b32 v74, v94
	ds_write_b32 v76, v95
	ds_write_b32 v78, v6
	ds_write_b32 v80, v96
	ds_write_b32 v82, v97
	ds_write_b32 v84, v98
	s_waitcnt vmcnt(0)
	ds_write_b32 v138, v137
	ds_write_b32 v140, v169
	ds_write_b32 v142, v186
	ds_write_b32 v144, v187
	ds_write_b32 v146, v188
	ds_write_b32 v148, v189
	ds_write_b32 v150, v190
	ds_write_b32 v152, v191
	ds_write_b32 v170, v192
	ds_write_b32 v172, v193
	ds_write_b32 v174, v194
	ds_write_b32 v176, v195
	ds_write_b32 v178, v106
	ds_write_b32 v180, v196
	ds_write_b32 v182, v197
	ds_write_b32 v184, v198
	s_waitcnt lgkmcnt(0)
	ds_read_b32 v5, v55
	ds_read_b32 v6, v55 offset:132
	ds_read_b32 v35, v55 offset:264
	ds_read_b32 v36, v55 offset:396
	ds_read_b32 v37, v55 offset:528
	ds_read_b32 v40, v55 offset:660
	ds_read_b32 v41, v55 offset:792
	ds_read_b32 v42, v55 offset:924
	s_waitcnt lgkmcnt(0)
	v_bfe_u32 v34, v5, 16, 1
	v_add3_u32 v5, v5, v34, s62
	v_bfe_u32 v34, v6, 16, 1
	v_lshrrev_b32_e32 v5, 16, v5
	v_add3_u32 v6, v6, v34, s62
	v_and_or_b32 v34, v6, s63, v5
	v_bfe_u32 v5, v35, 16, 1
	v_add3_u32 v5, v35, v5, s62
	v_bfe_u32 v6, v36, 16, 1
	v_lshrrev_b32_e32 v5, 16, v5
	v_add3_u32 v6, v36, v6, s62
	v_and_or_b32 v35, v6, s63, v5
	v_bfe_u32 v5, v37, 16, 1
	v_add3_u32 v5, v37, v5, s62
	v_bfe_u32 v6, v40, 16, 1
	v_lshrrev_b32_e32 v5, 16, v5
	v_add3_u32 v6, v40, v6, s62
	v_and_or_b32 v36, v6, s63, v5
	v_bfe_u32 v5, v41, 16, 1
	v_add3_u32 v5, v41, v5, s62
	v_bfe_u32 v6, v42, 16, 1
	v_lshrrev_b32_e32 v5, 16, v5
	v_add3_u32 v6, v42, v6, s62
	v_and_or_b32 v37, v6, s63, v5
	v_or_b32_e32 v5, s4, v33
	s_lshl_b32 s16, s5, 1
	v_mul_u32_u24_e32 v5, 0xc00, v5
	v_lshl_add_u64 v[38:39], v[16:17], 0, s[16:17]
	v_lshlrev_b32_e32 v6, 1, v5
	v_lshl_add_u64 v[40:41], v[38:39], 0, v[6:7]
	flat_store_dwordx4 v[40:41], v[34:37]
	ds_read_b32 v5, v55 offset:32
	ds_read_b32 v6, v55 offset:164
	ds_read_b32 v35, v55 offset:296
	ds_read_b32 v36, v55 offset:428
	ds_read_b32 v37, v55 offset:560
	ds_read_b32 v40, v55 offset:692
	ds_read_b32 v41, v55 offset:824
	ds_read_b32 v42, v55 offset:956
	s_waitcnt lgkmcnt(0)
	v_bfe_u32 v34, v5, 16, 1
	v_add3_u32 v5, v5, v34, s62
	v_bfe_u32 v34, v6, 16, 1
	v_lshrrev_b32_e32 v5, 16, v5
	v_add3_u32 v6, v6, v34, s62
	v_and_or_b32 v34, v6, s63, v5
	v_bfe_u32 v5, v35, 16, 1
	v_add3_u32 v5, v35, v5, s62
	v_bfe_u32 v6, v36, 16, 1
	v_lshrrev_b32_e32 v5, 16, v5
	v_add3_u32 v6, v36, v6, s62
	v_and_or_b32 v35, v6, s63, v5
	v_bfe_u32 v5, v37, 16, 1
	v_add3_u32 v5, v37, v5, s62
	v_bfe_u32 v6, v40, 16, 1
	v_lshrrev_b32_e32 v5, 16, v5
	v_add3_u32 v6, v40, v6, s62
	v_and_or_b32 v36, v6, s63, v5
	v_bfe_u32 v5, v41, 16, 1
	v_add3_u32 v5, v41, v5, s62
	v_bfe_u32 v6, v42, 16, 1
	v_lshrrev_b32_e32 v5, 16, v5
	v_add3_u32 v6, v42, v6, s62
	v_and_or_b32 v37, v6, s63, v5
	v_or_b32_e32 v5, s4, v56
	v_mul_u32_u24_e32 v5, 0xc00, v5
	v_lshlrev_b32_e32 v6, 1, v5
	v_lshl_add_u64 v[40:41], v[38:39], 0, v[6:7]
	flat_store_dwordx4 v[40:41], v[34:37]
	ds_read_b32 v5, v55 offset:64
	ds_read_b32 v6, v55 offset:196
	ds_read_b32 v35, v55 offset:328
	ds_read_b32 v36, v55 offset:460
	ds_read_b32 v37, v55 offset:592
	ds_read_b32 v40, v55 offset:724
	ds_read_b32 v41, v55 offset:856
	ds_read_b32 v42, v55 offset:988
	s_waitcnt lgkmcnt(0)
	v_bfe_u32 v34, v5, 16, 1
	v_add3_u32 v5, v5, v34, s62
	v_bfe_u32 v34, v6, 16, 1
	v_lshrrev_b32_e32 v5, 16, v5
	v_add3_u32 v6, v6, v34, s62
	v_and_or_b32 v34, v6, s63, v5
	v_bfe_u32 v5, v35, 16, 1
	v_add3_u32 v5, v35, v5, s62
	v_bfe_u32 v6, v36, 16, 1
	v_lshrrev_b32_e32 v5, 16, v5
	v_add3_u32 v6, v36, v6, s62
	v_and_or_b32 v35, v6, s63, v5
	v_bfe_u32 v5, v37, 16, 1
	v_add3_u32 v5, v37, v5, s62
	v_bfe_u32 v6, v40, 16, 1
	v_lshrrev_b32_e32 v5, 16, v5
	v_add3_u32 v6, v40, v6, s62
	v_and_or_b32 v36, v6, s63, v5
	v_bfe_u32 v5, v41, 16, 1
	v_add3_u32 v5, v41, v5, s62
	v_bfe_u32 v6, v42, 16, 1
	v_lshrrev_b32_e32 v5, 16, v5
	v_add3_u32 v6, v42, v6, s62
	v_and_or_b32 v37, v6, s63, v5
	v_or_b32_e32 v5, s4, v57
	v_mul_u32_u24_e32 v5, 0xc00, v5
	v_lshlrev_b32_e32 v6, 1, v5
	v_lshl_add_u64 v[40:41], v[38:39], 0, v[6:7]
	flat_store_dwordx4 v[40:41], v[34:37]
	ds_read_b32 v5, v55 offset:96
	ds_read_b32 v6, v55 offset:228
	ds_read_b32 v35, v55 offset:360
	ds_read_b32 v36, v55 offset:492
	ds_read_b32 v37, v55 offset:624
	ds_read_b32 v40, v55 offset:756
	ds_read_b32 v41, v55 offset:888
	ds_read_b32 v42, v55 offset:1020
	s_waitcnt lgkmcnt(0)
	v_bfe_u32 v34, v5, 16, 1
	v_add3_u32 v5, v5, v34, s62
	v_bfe_u32 v34, v6, 16, 1
	v_lshrrev_b32_e32 v5, 16, v5
	v_add3_u32 v6, v6, v34, s62
	v_and_or_b32 v34, v6, s63, v5
	v_bfe_u32 v5, v35, 16, 1
	v_add3_u32 v5, v35, v5, s62
	v_bfe_u32 v6, v36, 16, 1
	v_lshrrev_b32_e32 v5, 16, v5
	v_add3_u32 v6, v36, v6, s62
	v_and_or_b32 v35, v6, s63, v5
	v_bfe_u32 v5, v37, 16, 1
	v_add3_u32 v5, v37, v5, s62
	v_bfe_u32 v6, v40, 16, 1
	v_lshrrev_b32_e32 v5, 16, v5
	v_add3_u32 v6, v40, v6, s62
	v_and_or_b32 v36, v6, s63, v5
	v_bfe_u32 v5, v41, 16, 1
	v_add3_u32 v5, v41, v5, s62
	v_bfe_u32 v6, v42, 16, 1
	v_lshrrev_b32_e32 v5, 16, v5
	v_add3_u32 v6, v42, v6, s62
	v_and_or_b32 v37, v6, s63, v5
	v_or_b32_e32 v5, s4, v58
	v_mul_u32_u24_e32 v5, 0xc00, v5
	v_lshlrev_b32_e32 v6, 1, v5
	v_lshl_add_u64 v[38:39], v[38:39], 0, v[6:7]
	flat_store_dwordx4 v[38:39], v[34:37]
	s_waitcnt lgkmcnt(0)

.LBB0_59:
	s_lshl_b32 s56, s16, 1
	s_lshl_b32 s57, s18, 1
	v_or_b32_e32 v6, s57, v36
	s_add_i32 s58, s56, 4
	s_add_i32 s59, s57, 4
	v_mov_b32_e32 v41, v7
	s_add_i32 s70, s57, 8
	v_lshlrev_b64 v[70:71], 13, v[6:7]
	v_or_b32_e32 v40, s58, v5
	v_or_b32_e32 v6, s59, v36
	v_mov_b32_e32 v39, v7
	v_or_b32_e32 v38, s56, v5
	s_add_i32 s72, s57, 12
	v_lshlrev_b64 v[40:41], 13, v[40:41]
	v_lshlrev_b64 v[72:73], 13, v[6:7]
	v_or_b32_e32 v6, s70, v36
	s_add_i32 s69, s56, 8
	s_add_i32 s71, s56, 12
	s_add_i32 s74, s57, 16
	v_lshlrev_b64 v[38:39], 13, v[38:39]
	v_lshl_add_u64 v[70:71], v[34:35], 0, v[70:71]
	v_lshl_add_u64 v[40:41], v[34:35], 0, v[40:41]
	v_lshlrev_b64 v[74:75], 13, v[6:7]
	v_or_b32_e32 v6, s72, v36
	v_mov_b32_e32 v43, v7
	v_mov_b32_e32 v45, v7
	s_add_i32 s76, s57, 20
	v_or_b32_e32 v42, s69, v5
	v_or_b32_e32 v44, s71, v5
	v_lshl_add_u64 v[38:39], v[34:35], 0, v[38:39]
	v_lshl_add_u64 v[72:73], v[34:35], 0, v[72:73]
	global_load_dword v37, v[70:71], off
	global_load_dword v69, v[38:39], off
	global_load_dword v86, v[72:73], off
	global_load_dword v87, v[40:41], off
	v_lshlrev_b64 v[40:41], 13, v[6:7]
	v_or_b32_e32 v6, s74, v36
	s_add_i32 s73, s56, 16
	s_add_i32 s75, s56, 20
	s_add_i32 s78, s57, 24
	v_lshlrev_b64 v[42:43], 13, v[42:43]
	v_lshlrev_b64 v[44:45], 13, v[44:45]
	v_lshl_add_u64 v[38:39], v[34:35], 0, v[74:75]
	v_lshl_add_u64 v[40:41], v[34:35], 0, v[40:41]
	v_lshlrev_b64 v[70:71], 13, v[6:7]
	v_or_b32_e32 v6, s76, v36
	v_mov_b32_e32 v47, v7
	v_mov_b32_e32 v49, v7
	s_add_i32 s77, s56, 24
	s_add_i32 s79, s56, 28
	s_add_i32 s80, s57, 28
	v_or_b32_e32 v46, s73, v5
	v_or_b32_e32 v48, s75, v5
	v_lshl_add_u64 v[42:43], v[34:35], 0, v[42:43]
	v_lshl_add_u64 v[44:45], v[34:35], 0, v[44:45]
	global_load_dword v88, v[38:39], off
	global_load_dword v89, v[42:43], off
	global_load_dword v90, v[40:41], off
	global_load_dword v91, v[44:45], off
	v_lshlrev_b64 v[40:41], 13, v[6:7]
	v_or_b32_e32 v6, s78, v36
	v_mov_b32_e32 v51, v7
	v_mov_b32_e32 v53, v7
	v_or_b32_e32 v50, s77, v5
	v_or_b32_e32 v52, s79, v5
	v_lshlrev_b64 v[46:47], 13, v[46:47]
	v_lshlrev_b64 v[48:49], 13, v[48:49]
	v_lshl_add_u64 v[38:39], v[34:35], 0, v[70:71]
	v_lshl_add_u64 v[40:41], v[34:35], 0, v[40:41]
	v_lshlrev_b64 v[42:43], 13, v[6:7]
	v_or_b32_e32 v6, s80, v36
	v_lshlrev_b64 v[50:51], 13, v[50:51]
	v_lshlrev_b64 v[52:53], 13, v[52:53]
	v_lshl_add_u64 v[46:47], v[34:35], 0, v[46:47]
	v_lshl_add_u64 v[48:49], v[34:35], 0, v[48:49]
	global_load_dword v92, v[38:39], off
	global_load_dword v93, v[46:47], off
	global_load_dword v94, v[40:41], off
	global_load_dword v95, v[48:49], off
	v_lshl_add_u64 v[38:39], v[34:35], 0, v[42:43]
	v_lshlrev_b64 v[40:41], 13, v[6:7]
	v_lshl_add_u64 v[50:51], v[34:35], 0, v[50:51]
	v_lshl_add_u64 v[52:53], v[34:35], 0, v[52:53]
	v_lshl_add_u64 v[40:41], v[34:35], 0, v[40:41]
	global_load_dword v6, v[38:39], off
	global_load_dword v96, v[50:51], off
	global_load_dword v97, v[40:41], off
	global_load_dword v98, v[52:53], off
	v_or_b32_e32 v40, s56, v1
	v_or_b32_e32 v38, s57, v2
	s_add_i32 s18, s18, 16
	s_add_i32 s16, s16, 16
	s_add_i32 s19, s19, -16
	v_mad_u64_u32 v[38:39], s[56:57], v38, s13, v[4:5]
	v_mad_u64_u32 v[40:41], s[56:57], v40, s13, v[4:5]
	v_or_b32_e32 v39, s58, v1
	v_or_b32_e32 v41, s59, v2
	v_or_b32_e32 v48, s69, v1
	v_or_b32_e32 v46, s70, v2
	v_or_b32_e32 v52, s71, v1
	v_or_b32_e32 v50, s72, v2
	v_or_b32_e32 v72, s73, v1
	v_or_b32_e32 v70, s74, v2
	v_or_b32_e32 v76, s75, v1
	v_or_b32_e32 v74, s76, v2
	v_or_b32_e32 v80, s77, v1
	v_or_b32_e32 v78, s78, v2
	v_or_b32_e32 v84, s79, v1
	v_or_b32_e32 v82, s80, v2
	s_cmp_lg_u32 s19, 0
	v_mad_u64_u32 v[42:43], s[56:57], v41, s13, v[4:5]
	v_mad_u64_u32 v[44:45], s[56:57], v39, s13, v[4:5]
	v_mad_u64_u32 v[46:47], s[56:57], v46, s13, v[4:5]
	v_mad_u64_u32 v[48:49], s[56:57], v48, s13, v[4:5]
	v_mad_u64_u32 v[50:51], s[56:57], v50, s13, v[4:5]
	v_mad_u64_u32 v[52:53], s[56:57], v52, s13, v[4:5]
	v_mad_u64_u32 v[70:71], s[56:57], v70, s13, v[4:5]
	v_mad_u64_u32 v[72:73], s[56:57], v72, s13, v[4:5]
	v_mad_u64_u32 v[74:75], s[56:57], v74, s13, v[4:5]
	v_mad_u64_u32 v[76:77], s[56:57], v76, s13, v[4:5]
	v_mad_u64_u32 v[78:79], s[56:57], v78, s13, v[4:5]
	v_mad_u64_u32 v[80:81], s[56:57], v80, s13, v[4:5]
	v_mad_u64_u32 v[82:83], s[56:57], v82, s13, v[4:5]
	v_mad_u64_u32 v[84:85], s[56:57], v84, s13, v[4:5]
	v_mov_b32_e32 v107, v7
	s_lshl_b32 s56, s16, 1
	s_lshl_b32 s57, s18, 1
	v_or_b32_e32 v106, s57, v36
	s_add_i32 s58, s56, 4
	s_add_i32 s59, s57, 4
	v_mov_b32_e32 v141, v107
	s_add_i32 s70, s57, 8
	v_lshlrev_b64 v[170:171], 13, v[106:107]
	v_or_b32_e32 v140, s58, v5
	v_or_b32_e32 v106, s59, v36
	v_mov_b32_e32 v139, v107
	v_or_b32_e32 v138, s56, v5
	s_add_i32 s72, s57, 12
	v_lshlrev_b64 v[140:141], 13, v[140:141]
	v_lshlrev_b64 v[172:173], 13, v[106:107]
	v_or_b32_e32 v106, s70, v36
	s_add_i32 s69, s56, 8
	s_add_i32 s71, s56, 12
	s_add_i32 s74, s57, 16
	v_lshlrev_b64 v[138:139], 13, v[138:139]
	v_lshl_add_u64 v[170:171], v[34:35], 0, v[170:171]
	v_lshl_add_u64 v[140:141], v[34:35], 0, v[140:141]
	v_lshlrev_b64 v[174:175], 13, v[106:107]
	v_or_b32_e32 v106, s72, v36
	v_mov_b32_e32 v143, v107
	v_mov_b32_e32 v145, v107
	s_add_i32 s76, s57, 20
	v_or_b32_e32 v142, s69, v5
	v_or_b32_e32 v144, s71, v5
	v_lshl_add_u64 v[138:139], v[34:35], 0, v[138:139]
	v_lshl_add_u64 v[172:173], v[34:35], 0, v[172:173]
	global_load_dword v137, v[170:171], off
	global_load_dword v169, v[138:139], off
	global_load_dword v186, v[172:173], off
	global_load_dword v187, v[140:141], off
	v_lshlrev_b64 v[140:141], 13, v[106:107]
	v_or_b32_e32 v106, s74, v36
	s_add_i32 s73, s56, 16
	s_add_i32 s75, s56, 20
	s_add_i32 s78, s57, 24
	v_lshlrev_b64 v[142:143], 13, v[142:143]
	v_lshlrev_b64 v[144:145], 13, v[144:145]
	v_lshl_add_u64 v[138:139], v[34:35], 0, v[174:175]
	v_lshl_add_u64 v[140:141], v[34:35], 0, v[140:141]
	v_lshlrev_b64 v[170:171], 13, v[106:107]
	v_or_b32_e32 v106, s76, v36
	v_mov_b32_e32 v147, v107
	v_mov_b32_e32 v149, v107
	s_add_i32 s77, s56, 24
	s_add_i32 s79, s56, 28
	s_add_i32 s80, s57, 28
	v_or_b32_e32 v146, s73, v5
	v_or_b32_e32 v148, s75, v5
	v_lshl_add_u64 v[142:143], v[34:35], 0, v[142:143]
	v_lshl_add_u64 v[144:145], v[34:35], 0, v[144:145]
	global_load_dword v188, v[138:139], off
	global_load_dword v189, v[142:143], off
	global_load_dword v190, v[140:141], off
	global_load_dword v191, v[144:145], off
	v_lshlrev_b64 v[140:141], 13, v[106:107]
	v_or_b32_e32 v106, s78, v36
	v_mov_b32_e32 v151, v107
	v_mov_b32_e32 v153, v107
	v_or_b32_e32 v150, s77, v5
	v_or_b32_e32 v152, s79, v5
	v_lshlrev_b64 v[146:147], 13, v[146:147]
	v_lshlrev_b64 v[148:149], 13, v[148:149]
	v_lshl_add_u64 v[138:139], v[34:35], 0, v[170:171]
	v_lshl_add_u64 v[140:141], v[34:35], 0, v[140:141]
	v_lshlrev_b64 v[142:143], 13, v[106:107]
	v_or_b32_e32 v106, s80, v36
	v_lshlrev_b64 v[150:151], 13, v[150:151]
	v_lshlrev_b64 v[152:153], 13, v[152:153]
	v_lshl_add_u64 v[146:147], v[34:35], 0, v[146:147]
	v_lshl_add_u64 v[148:149], v[34:35], 0, v[148:149]
	global_load_dword v192, v[138:139], off
	global_load_dword v193, v[146:147], off
	global_load_dword v194, v[140:141], off
	global_load_dword v195, v[148:149], off
	v_lshl_add_u64 v[138:139], v[34:35], 0, v[142:143]
	v_lshlrev_b64 v[140:141], 13, v[106:107]
	v_lshl_add_u64 v[150:151], v[34:35], 0, v[150:151]
	v_lshl_add_u64 v[152:153], v[34:35], 0, v[152:153]
	v_lshl_add_u64 v[140:141], v[34:35], 0, v[140:141]
	global_load_dword v106, v[138:139], off
	global_load_dword v196, v[150:151], off
	global_load_dword v197, v[140:141], off
	global_load_dword v198, v[152:153], off
	v_or_b32_e32 v140, s56, v1
	v_or_b32_e32 v138, s57, v2
	s_add_i32 s18, s18, 16
	s_add_i32 s16, s16, 16
	s_add_i32 s19, s19, -16
	v_mad_u64_u32 v[138:139], s[56:57], v138, s13, v[4:5]
	v_mad_u64_u32 v[140:141], s[56:57], v140, s13, v[4:5]
	v_or_b32_e32 v139, s58, v1
	v_or_b32_e32 v141, s59, v2
	v_or_b32_e32 v148, s69, v1
	v_or_b32_e32 v146, s70, v2
	v_or_b32_e32 v152, s71, v1
	v_or_b32_e32 v150, s72, v2
	v_or_b32_e32 v172, s73, v1
	v_or_b32_e32 v170, s74, v2
	v_or_b32_e32 v176, s75, v1
	v_or_b32_e32 v174, s76, v2
	v_or_b32_e32 v180, s77, v1
	v_or_b32_e32 v178, s78, v2
	v_or_b32_e32 v184, s79, v1
	v_or_b32_e32 v182, s80, v2
	s_cmp_lg_u32 s19, 0
	v_mad_u64_u32 v[142:143], s[56:57], v141, s13, v[4:5]
	v_mad_u64_u32 v[144:145], s[56:57], v139, s13, v[4:5]
	v_mad_u64_u32 v[146:147], s[56:57], v146, s13, v[4:5]
	v_mad_u64_u32 v[148:149], s[56:57], v148, s13, v[4:5]
	v_mad_u64_u32 v[150:151], s[56:57], v150, s13, v[4:5]
	v_mad_u64_u32 v[152:153], s[56:57], v152, s13, v[4:5]
	v_mad_u64_u32 v[170:171], s[56:57], v170, s13, v[4:5]
	v_mad_u64_u32 v[172:173], s[56:57], v172, s13, v[4:5]
	v_mad_u64_u32 v[174:175], s[56:57], v174, s13, v[4:5]
	v_mad_u64_u32 v[176:177], s[56:57], v176, s13, v[4:5]
	v_mad_u64_u32 v[178:179], s[56:57], v178, s13, v[4:5]
	v_mad_u64_u32 v[180:181], s[56:57], v180, s13, v[4:5]
	v_mad_u64_u32 v[182:183], s[56:57], v182, s13, v[4:5]
	v_mad_u64_u32 v[184:185], s[56:57], v184, s13, v[4:5]
	s_waitcnt vmcnt(16)
	ds_write_b32 v38, v37
	ds_write_b32 v40, v69
	ds_write_b32 v42, v86
	ds_write_b32 v44, v87
	ds_write_b32 v46, v88
	ds_write_b32 v48, v89
	ds_write_b32 v50, v90
	ds_write_b32 v52, v91
	ds_write_b32 v70, v92
	ds_write_b32 v72, v93
	ds_write_b32 v74, v94
	ds_write_b32 v76, v95
	ds_write_b32 v78, v6
	ds_write_b32 v80, v96
	ds_write_b32 v82, v97
	ds_write_b32 v84, v98
	s_waitcnt vmcnt(0)
	ds_write_b32 v138, v137
	ds_write_b32 v140, v169
	ds_write_b32 v142, v186
	ds_write_b32 v144, v187
	ds_write_b32 v146, v188
	ds_write_b32 v148, v189
	ds_write_b32 v150, v190
	ds_write_b32 v152, v191
	ds_write_b32 v170, v192
	ds_write_b32 v172, v193
	ds_write_b32 v174, v194
	ds_write_b32 v176, v195
	ds_write_b32 v178, v106
	ds_write_b32 v180, v196
	ds_write_b32 v182, v197
	ds_write_b32 v184, v198
	s_waitcnt lgkmcnt(0)
	ds_read_b32 v5, v55
	ds_read_b32 v6, v55 offset:132
	ds_read_b32 v35, v55 offset:264
	ds_read_b32 v36, v55 offset:396
	ds_read_b32 v37, v55 offset:528
	ds_read_b32 v40, v55 offset:660
	ds_read_b32 v41, v55 offset:792
	ds_read_b32 v42, v55 offset:924
	s_waitcnt lgkmcnt(0)
	v_bfe_u32 v34, v5, 16, 1
	v_add3_u32 v5, v5, v34, s62
	v_bfe_u32 v34, v6, 16, 1
	v_lshrrev_b32_e32 v5, 16, v5
	v_add3_u32 v6, v6, v34, s62
	v_and_or_b32 v34, v6, s63, v5
	v_bfe_u32 v5, v35, 16, 1
	v_add3_u32 v5, v35, v5, s62
	v_bfe_u32 v6, v36, 16, 1
	v_lshrrev_b32_e32 v5, 16, v5
	v_add3_u32 v6, v36, v6, s62
	v_and_or_b32 v35, v6, s63, v5
	v_bfe_u32 v5, v37, 16, 1
	v_add3_u32 v5, v37, v5, s62
	v_bfe_u32 v6, v40, 16, 1
	v_lshrrev_b32_e32 v5, 16, v5
	v_add3_u32 v6, v40, v6, s62
	v_and_or_b32 v36, v6, s63, v5
	v_bfe_u32 v5, v41, 16, 1
	v_add3_u32 v5, v41, v5, s62
	v_bfe_u32 v6, v42, 16, 1
	v_lshrrev_b32_e32 v5, 16, v5
	v_add3_u32 v6, v42, v6, s62
	v_and_or_b32 v37, v6, s63, v5
	v_or_b32_e32 v5, s4, v33
	s_lshl_b32 s16, s5, 1
	v_mul_u32_u24_e32 v5, 0xc00, v5
	v_lshl_add_u64 v[38:39], v[18:19], 0, s[16:17]
	v_lshlrev_b32_e32 v6, 1, v5
	v_lshl_add_u64 v[40:41], v[38:39], 0, v[6:7]
	flat_store_dwordx4 v[40:41], v[34:37]
	ds_read_b32 v5, v55 offset:32
	ds_read_b32 v6, v55 offset:164
	ds_read_b32 v35, v55 offset:296
	ds_read_b32 v36, v55 offset:428
	ds_read_b32 v37, v55 offset:560
	ds_read_b32 v40, v55 offset:692
	ds_read_b32 v41, v55 offset:824
	ds_read_b32 v42, v55 offset:956
	s_waitcnt lgkmcnt(0)
	v_bfe_u32 v34, v5, 16, 1
	v_add3_u32 v5, v5, v34, s62
	v_bfe_u32 v34, v6, 16, 1
	v_lshrrev_b32_e32 v5, 16, v5
	v_add3_u32 v6, v6, v34, s62
	v_and_or_b32 v34, v6, s63, v5
	v_bfe_u32 v5, v35, 16, 1
	v_add3_u32 v5, v35, v5, s62
	v_bfe_u32 v6, v36, 16, 1
	v_lshrrev_b32_e32 v5, 16, v5
	v_add3_u32 v6, v36, v6, s62
	v_and_or_b32 v35, v6, s63, v5
	v_bfe_u32 v5, v37, 16, 1
	v_add3_u32 v5, v37, v5, s62
	v_bfe_u32 v6, v40, 16, 1
	v_lshrrev_b32_e32 v5, 16, v5
	v_add3_u32 v6, v40, v6, s62
	v_and_or_b32 v36, v6, s63, v5
	v_bfe_u32 v5, v41, 16, 1
	v_add3_u32 v5, v41, v5, s62
	v_bfe_u32 v6, v42, 16, 1
	v_lshrrev_b32_e32 v5, 16, v5
	v_add3_u32 v6, v42, v6, s62
	v_and_or_b32 v37, v6, s63, v5
	v_or_b32_e32 v5, s4, v56
	v_mul_u32_u24_e32 v5, 0xc00, v5
	v_lshlrev_b32_e32 v6, 1, v5
	v_lshl_add_u64 v[40:41], v[38:39], 0, v[6:7]
	flat_store_dwordx4 v[40:41], v[34:37]
	ds_read_b32 v5, v55 offset:64
	ds_read_b32 v6, v55 offset:196
	ds_read_b32 v35, v55 offset:328
	ds_read_b32 v36, v55 offset:460
	ds_read_b32 v37, v55 offset:592
	ds_read_b32 v40, v55 offset:724
	ds_read_b32 v41, v55 offset:856
	ds_read_b32 v42, v55 offset:988
	s_waitcnt lgkmcnt(0)
	v_bfe_u32 v34, v5, 16, 1
	v_add3_u32 v5, v5, v34, s62
	v_bfe_u32 v34, v6, 16, 1
	v_lshrrev_b32_e32 v5, 16, v5
	v_add3_u32 v6, v6, v34, s62
	v_and_or_b32 v34, v6, s63, v5
	v_bfe_u32 v5, v35, 16, 1
	v_add3_u32 v5, v35, v5, s62
	v_bfe_u32 v6, v36, 16, 1
	v_lshrrev_b32_e32 v5, 16, v5
	v_add3_u32 v6, v36, v6, s62
	v_and_or_b32 v35, v6, s63, v5
	v_bfe_u32 v5, v37, 16, 1
	v_add3_u32 v5, v37, v5, s62
	v_bfe_u32 v6, v40, 16, 1
	v_lshrrev_b32_e32 v5, 16, v5
	v_add3_u32 v6, v40, v6, s62
	v_and_or_b32 v36, v6, s63, v5
	v_bfe_u32 v5, v41, 16, 1
	v_add3_u32 v5, v41, v5, s62
	v_bfe_u32 v6, v42, 16, 1
	v_lshrrev_b32_e32 v5, 16, v5
	v_add3_u32 v6, v42, v6, s62
	v_and_or_b32 v37, v6, s63, v5
	v_or_b32_e32 v5, s4, v57
	v_mul_u32_u24_e32 v5, 0xc00, v5
	v_lshlrev_b32_e32 v6, 1, v5
	v_lshl_add_u64 v[40:41], v[38:39], 0, v[6:7]
	flat_store_dwordx4 v[40:41], v[34:37]
	ds_read_b32 v5, v55 offset:96
	ds_read_b32 v6, v55 offset:228
	ds_read_b32 v35, v55 offset:360
	ds_read_b32 v36, v55 offset:492
	ds_read_b32 v37, v55 offset:624
	ds_read_b32 v40, v55 offset:756
	ds_read_b32 v41, v55 offset:888
	ds_read_b32 v42, v55 offset:1020
	s_waitcnt lgkmcnt(0)
	v_bfe_u32 v34, v5, 16, 1
	v_add3_u32 v5, v5, v34, s62
	v_bfe_u32 v34, v6, 16, 1
	v_lshrrev_b32_e32 v5, 16, v5
	v_add3_u32 v6, v6, v34, s62
	v_and_or_b32 v34, v6, s63, v5
	v_bfe_u32 v5, v35, 16, 1
	v_add3_u32 v5, v35, v5, s62
	v_bfe_u32 v6, v36, 16, 1
	v_lshrrev_b32_e32 v5, 16, v5
	v_add3_u32 v6, v36, v6, s62
	v_and_or_b32 v35, v6, s63, v5
	v_bfe_u32 v5, v37, 16, 1
	v_add3_u32 v5, v37, v5, s62
	v_bfe_u32 v6, v40, 16, 1
	v_lshrrev_b32_e32 v5, 16, v5
	v_add3_u32 v6, v40, v6, s62
	v_and_or_b32 v36, v6, s63, v5
	v_bfe_u32 v5, v41, 16, 1
	v_add3_u32 v5, v41, v5, s62
	v_bfe_u32 v6, v42, 16, 1
	v_lshrrev_b32_e32 v5, 16, v5
	v_add3_u32 v6, v42, v6, s62
	v_and_or_b32 v37, v6, s63, v5
	v_or_b32_e32 v5, s4, v58
	v_mul_u32_u24_e32 v5, 0xc00, v5
	v_lshlrev_b32_e32 v6, 1, v5
	v_lshl_add_u64 v[38:39], v[38:39], 0, v[6:7]
	flat_store_dwordx4 v[38:39], v[34:37]
	s_waitcnt lgkmcnt(0)

.LBB0_64:
	s_lshl_b32 s56, s16, 1
	s_lshl_b32 s57, s18, 1
	v_or_b32_e32 v6, s57, v36
	s_add_i32 s58, s56, 4
	s_add_i32 s59, s57, 4
	v_mov_b32_e32 v41, v7
	s_add_i32 s70, s57, 8
	v_lshlrev_b64 v[70:71], 13, v[6:7]
	v_or_b32_e32 v40, s58, v5
	v_or_b32_e32 v6, s59, v36
	v_mov_b32_e32 v39, v7
	v_or_b32_e32 v38, s56, v5
	s_add_i32 s72, s57, 12
	v_lshlrev_b64 v[40:41], 13, v[40:41]
	v_lshlrev_b64 v[72:73], 13, v[6:7]
	v_or_b32_e32 v6, s70, v36
	s_add_i32 s69, s56, 8
	s_add_i32 s71, s56, 12
	s_add_i32 s74, s57, 16
	v_lshlrev_b64 v[38:39], 13, v[38:39]
	v_lshl_add_u64 v[70:71], v[34:35], 0, v[70:71]
	v_lshl_add_u64 v[40:41], v[34:35], 0, v[40:41]
	v_lshlrev_b64 v[74:75], 13, v[6:7]
	v_or_b32_e32 v6, s72, v36
	v_mov_b32_e32 v43, v7
	v_mov_b32_e32 v45, v7
	s_add_i32 s76, s57, 20
	v_or_b32_e32 v42, s69, v5
	v_or_b32_e32 v44, s71, v5
	v_lshl_add_u64 v[38:39], v[34:35], 0, v[38:39]
	v_lshl_add_u64 v[72:73], v[34:35], 0, v[72:73]
	global_load_dword v37, v[70:71], off
	global_load_dword v69, v[38:39], off
	global_load_dword v86, v[72:73], off
	global_load_dword v87, v[40:41], off
	v_lshlrev_b64 v[40:41], 13, v[6:7]
	v_or_b32_e32 v6, s74, v36
	s_add_i32 s73, s56, 16
	s_add_i32 s75, s56, 20
	s_add_i32 s78, s57, 24
	v_lshlrev_b64 v[42:43], 13, v[42:43]
	v_lshlrev_b64 v[44:45], 13, v[44:45]
	v_lshl_add_u64 v[38:39], v[34:35], 0, v[74:75]
	v_lshl_add_u64 v[40:41], v[34:35], 0, v[40:41]
	v_lshlrev_b64 v[70:71], 13, v[6:7]
	v_or_b32_e32 v6, s76, v36
	v_mov_b32_e32 v47, v7
	v_mov_b32_e32 v49, v7
	s_add_i32 s77, s56, 24
	s_add_i32 s79, s56, 28
	s_add_i32 s80, s57, 28
	v_or_b32_e32 v46, s73, v5
	v_or_b32_e32 v48, s75, v5
	v_lshl_add_u64 v[42:43], v[34:35], 0, v[42:43]
	v_lshl_add_u64 v[44:45], v[34:35], 0, v[44:45]
	global_load_dword v88, v[38:39], off
	global_load_dword v89, v[42:43], off
	global_load_dword v90, v[40:41], off
	global_load_dword v91, v[44:45], off
	v_lshlrev_b64 v[40:41], 13, v[6:7]
	v_or_b32_e32 v6, s78, v36
	v_mov_b32_e32 v51, v7
	v_mov_b32_e32 v53, v7
	v_or_b32_e32 v50, s77, v5
	v_or_b32_e32 v52, s79, v5
	v_lshlrev_b64 v[46:47], 13, v[46:47]
	v_lshlrev_b64 v[48:49], 13, v[48:49]
	v_lshl_add_u64 v[38:39], v[34:35], 0, v[70:71]
	v_lshl_add_u64 v[40:41], v[34:35], 0, v[40:41]
	v_lshlrev_b64 v[42:43], 13, v[6:7]
	v_or_b32_e32 v6, s80, v36
	v_lshlrev_b64 v[50:51], 13, v[50:51]
	v_lshlrev_b64 v[52:53], 13, v[52:53]
	v_lshl_add_u64 v[46:47], v[34:35], 0, v[46:47]
	v_lshl_add_u64 v[48:49], v[34:35], 0, v[48:49]
	global_load_dword v92, v[38:39], off
	global_load_dword v93, v[46:47], off
	global_load_dword v94, v[40:41], off
	global_load_dword v95, v[48:49], off
	v_lshl_add_u64 v[38:39], v[34:35], 0, v[42:43]
	v_lshlrev_b64 v[40:41], 13, v[6:7]
	v_lshl_add_u64 v[50:51], v[34:35], 0, v[50:51]
	v_lshl_add_u64 v[52:53], v[34:35], 0, v[52:53]
	v_lshl_add_u64 v[40:41], v[34:35], 0, v[40:41]
	global_load_dword v6, v[38:39], off
	global_load_dword v96, v[50:51], off
	global_load_dword v97, v[40:41], off
	global_load_dword v98, v[52:53], off
	v_or_b32_e32 v40, s56, v1
	v_or_b32_e32 v38, s57, v2
	s_add_i32 s18, s18, 16
	s_add_i32 s16, s16, 16
	s_add_i32 s19, s19, -16
	v_mad_u64_u32 v[38:39], s[56:57], v38, s13, v[4:5]
	v_mad_u64_u32 v[40:41], s[56:57], v40, s13, v[4:5]
	v_or_b32_e32 v39, s58, v1
	v_or_b32_e32 v41, s59, v2
	v_or_b32_e32 v48, s69, v1
	v_or_b32_e32 v46, s70, v2
	v_or_b32_e32 v52, s71, v1
	v_or_b32_e32 v50, s72, v2
	v_or_b32_e32 v72, s73, v1
	v_or_b32_e32 v70, s74, v2
	v_or_b32_e32 v76, s75, v1
	v_or_b32_e32 v74, s76, v2
	v_or_b32_e32 v80, s77, v1
	v_or_b32_e32 v78, s78, v2
	v_or_b32_e32 v84, s79, v1
	v_or_b32_e32 v82, s80, v2
	s_cmp_lg_u32 s19, 0
	v_mad_u64_u32 v[42:43], s[56:57], v41, s13, v[4:5]
	v_mad_u64_u32 v[44:45], s[56:57], v39, s13, v[4:5]
	v_mad_u64_u32 v[46:47], s[56:57], v46, s13, v[4:5]
	v_mad_u64_u32 v[48:49], s[56:57], v48, s13, v[4:5]
	v_mad_u64_u32 v[50:51], s[56:57], v50, s13, v[4:5]
	v_mad_u64_u32 v[52:53], s[56:57], v52, s13, v[4:5]
	v_mad_u64_u32 v[70:71], s[56:57], v70, s13, v[4:5]
	v_mad_u64_u32 v[72:73], s[56:57], v72, s13, v[4:5]
	v_mad_u64_u32 v[74:75], s[56:57], v74, s13, v[4:5]
	v_mad_u64_u32 v[76:77], s[56:57], v76, s13, v[4:5]
	v_mad_u64_u32 v[78:79], s[56:57], v78, s13, v[4:5]
	v_mad_u64_u32 v[80:81], s[56:57], v80, s13, v[4:5]
	v_mad_u64_u32 v[82:83], s[56:57], v82, s13, v[4:5]
	v_mad_u64_u32 v[84:85], s[56:57], v84, s13, v[4:5]
	v_mov_b32_e32 v107, v7
	s_lshl_b32 s56, s16, 1
	s_lshl_b32 s57, s18, 1
	v_or_b32_e32 v106, s57, v36
	s_add_i32 s58, s56, 4
	s_add_i32 s59, s57, 4
	v_mov_b32_e32 v141, v107
	s_add_i32 s70, s57, 8
	v_lshlrev_b64 v[170:171], 13, v[106:107]
	v_or_b32_e32 v140, s58, v5
	v_or_b32_e32 v106, s59, v36
	v_mov_b32_e32 v139, v107
	v_or_b32_e32 v138, s56, v5
	s_add_i32 s72, s57, 12
	v_lshlrev_b64 v[140:141], 13, v[140:141]
	v_lshlrev_b64 v[172:173], 13, v[106:107]
	v_or_b32_e32 v106, s70, v36
	s_add_i32 s69, s56, 8
	s_add_i32 s71, s56, 12
	s_add_i32 s74, s57, 16
	v_lshlrev_b64 v[138:139], 13, v[138:139]
	v_lshl_add_u64 v[170:171], v[34:35], 0, v[170:171]
	v_lshl_add_u64 v[140:141], v[34:35], 0, v[140:141]
	v_lshlrev_b64 v[174:175], 13, v[106:107]
	v_or_b32_e32 v106, s72, v36
	v_mov_b32_e32 v143, v107
	v_mov_b32_e32 v145, v107
	s_add_i32 s76, s57, 20
	v_or_b32_e32 v142, s69, v5
	v_or_b32_e32 v144, s71, v5
	v_lshl_add_u64 v[138:139], v[34:35], 0, v[138:139]
	v_lshl_add_u64 v[172:173], v[34:35], 0, v[172:173]
	global_load_dword v137, v[170:171], off
	global_load_dword v169, v[138:139], off
	global_load_dword v186, v[172:173], off
	global_load_dword v187, v[140:141], off
	v_lshlrev_b64 v[140:141], 13, v[106:107]
	v_or_b32_e32 v106, s74, v36
	s_add_i32 s73, s56, 16
	s_add_i32 s75, s56, 20
	s_add_i32 s78, s57, 24
	v_lshlrev_b64 v[142:143], 13, v[142:143]
	v_lshlrev_b64 v[144:145], 13, v[144:145]
	v_lshl_add_u64 v[138:139], v[34:35], 0, v[174:175]
	v_lshl_add_u64 v[140:141], v[34:35], 0, v[140:141]
	v_lshlrev_b64 v[170:171], 13, v[106:107]
	v_or_b32_e32 v106, s76, v36
	v_mov_b32_e32 v147, v107
	v_mov_b32_e32 v149, v107
	s_add_i32 s77, s56, 24
	s_add_i32 s79, s56, 28
	s_add_i32 s80, s57, 28
	v_or_b32_e32 v146, s73, v5
	v_or_b32_e32 v148, s75, v5
	v_lshl_add_u64 v[142:143], v[34:35], 0, v[142:143]
	v_lshl_add_u64 v[144:145], v[34:35], 0, v[144:145]
	global_load_dword v188, v[138:139], off
	global_load_dword v189, v[142:143], off
	global_load_dword v190, v[140:141], off
	global_load_dword v191, v[144:145], off
	v_lshlrev_b64 v[140:141], 13, v[106:107]
	v_or_b32_e32 v106, s78, v36
	v_mov_b32_e32 v151, v107
	v_mov_b32_e32 v153, v107
	v_or_b32_e32 v150, s77, v5
	v_or_b32_e32 v152, s79, v5
	v_lshlrev_b64 v[146:147], 13, v[146:147]
	v_lshlrev_b64 v[148:149], 13, v[148:149]
	v_lshl_add_u64 v[138:139], v[34:35], 0, v[170:171]
	v_lshl_add_u64 v[140:141], v[34:35], 0, v[140:141]
	v_lshlrev_b64 v[142:143], 13, v[106:107]
	v_or_b32_e32 v106, s80, v36
	v_lshlrev_b64 v[150:151], 13, v[150:151]
	v_lshlrev_b64 v[152:153], 13, v[152:153]
	v_lshl_add_u64 v[146:147], v[34:35], 0, v[146:147]
	v_lshl_add_u64 v[148:149], v[34:35], 0, v[148:149]
	global_load_dword v192, v[138:139], off
	global_load_dword v193, v[146:147], off
	global_load_dword v194, v[140:141], off
	global_load_dword v195, v[148:149], off
	v_lshl_add_u64 v[138:139], v[34:35], 0, v[142:143]
	v_lshlrev_b64 v[140:141], 13, v[106:107]
	v_lshl_add_u64 v[150:151], v[34:35], 0, v[150:151]
	v_lshl_add_u64 v[152:153], v[34:35], 0, v[152:153]
	v_lshl_add_u64 v[140:141], v[34:35], 0, v[140:141]
	global_load_dword v106, v[138:139], off
	global_load_dword v196, v[150:151], off
	global_load_dword v197, v[140:141], off
	global_load_dword v198, v[152:153], off
	v_or_b32_e32 v140, s56, v1
	v_or_b32_e32 v138, s57, v2
	s_add_i32 s18, s18, 16
	s_add_i32 s16, s16, 16
	s_add_i32 s19, s19, -16
	v_mad_u64_u32 v[138:139], s[56:57], v138, s13, v[4:5]
	v_mad_u64_u32 v[140:141], s[56:57], v140, s13, v[4:5]
	v_or_b32_e32 v139, s58, v1
	v_or_b32_e32 v141, s59, v2
	v_or_b32_e32 v148, s69, v1
	v_or_b32_e32 v146, s70, v2
	v_or_b32_e32 v152, s71, v1
	v_or_b32_e32 v150, s72, v2
	v_or_b32_e32 v172, s73, v1
	v_or_b32_e32 v170, s74, v2
	v_or_b32_e32 v176, s75, v1
	v_or_b32_e32 v174, s76, v2
	v_or_b32_e32 v180, s77, v1
	v_or_b32_e32 v178, s78, v2
	v_or_b32_e32 v184, s79, v1
	v_or_b32_e32 v182, s80, v2
	s_cmp_lg_u32 s19, 0
	v_mad_u64_u32 v[142:143], s[56:57], v141, s13, v[4:5]
	v_mad_u64_u32 v[144:145], s[56:57], v139, s13, v[4:5]
	v_mad_u64_u32 v[146:147], s[56:57], v146, s13, v[4:5]
	v_mad_u64_u32 v[148:149], s[56:57], v148, s13, v[4:5]
	v_mad_u64_u32 v[150:151], s[56:57], v150, s13, v[4:5]
	v_mad_u64_u32 v[152:153], s[56:57], v152, s13, v[4:5]
	v_mad_u64_u32 v[170:171], s[56:57], v170, s13, v[4:5]
	v_mad_u64_u32 v[172:173], s[56:57], v172, s13, v[4:5]
	v_mad_u64_u32 v[174:175], s[56:57], v174, s13, v[4:5]
	v_mad_u64_u32 v[176:177], s[56:57], v176, s13, v[4:5]
	v_mad_u64_u32 v[178:179], s[56:57], v178, s13, v[4:5]
	v_mad_u64_u32 v[180:181], s[56:57], v180, s13, v[4:5]
	v_mad_u64_u32 v[182:183], s[56:57], v182, s13, v[4:5]
	v_mad_u64_u32 v[184:185], s[56:57], v184, s13, v[4:5]
	s_waitcnt vmcnt(16)
	ds_write_b32 v38, v37
	ds_write_b32 v40, v69
	ds_write_b32 v42, v86
	ds_write_b32 v44, v87
	ds_write_b32 v46, v88
	ds_write_b32 v48, v89
	ds_write_b32 v50, v90
	ds_write_b32 v52, v91
	ds_write_b32 v70, v92
	ds_write_b32 v72, v93
	ds_write_b32 v74, v94
	ds_write_b32 v76, v95
	ds_write_b32 v78, v6
	ds_write_b32 v80, v96
	ds_write_b32 v82, v97
	ds_write_b32 v84, v98
	s_waitcnt vmcnt(0)
	ds_write_b32 v138, v137
	ds_write_b32 v140, v169
	ds_write_b32 v142, v186
	ds_write_b32 v144, v187
	ds_write_b32 v146, v188
	ds_write_b32 v148, v189
	ds_write_b32 v150, v190
	ds_write_b32 v152, v191
	ds_write_b32 v170, v192
	ds_write_b32 v172, v193
	ds_write_b32 v174, v194
	ds_write_b32 v176, v195
	ds_write_b32 v178, v106
	ds_write_b32 v180, v196
	ds_write_b32 v182, v197
	ds_write_b32 v184, v198
	s_waitcnt lgkmcnt(0)
	ds_read_b32 v5, v55
	ds_read_b32 v6, v55 offset:132
	ds_read_b32 v35, v55 offset:264
	ds_read_b32 v36, v55 offset:396
	ds_read_b32 v37, v55 offset:528
	ds_read_b32 v40, v55 offset:660
	ds_read_b32 v41, v55 offset:792
	ds_read_b32 v42, v55 offset:924
	s_waitcnt lgkmcnt(0)
	v_bfe_u32 v34, v5, 16, 1
	v_add3_u32 v5, v5, v34, s62
	v_bfe_u32 v34, v6, 16, 1
	v_lshrrev_b32_e32 v5, 16, v5
	v_add3_u32 v6, v6, v34, s62
	v_and_or_b32 v34, v6, s63, v5
	v_bfe_u32 v5, v35, 16, 1
	v_add3_u32 v5, v35, v5, s62
	v_bfe_u32 v6, v36, 16, 1
	v_lshrrev_b32_e32 v5, 16, v5
	v_add3_u32 v6, v36, v6, s62
	v_and_or_b32 v35, v6, s63, v5
	v_bfe_u32 v5, v37, 16, 1
	v_add3_u32 v5, v37, v5, s62
	v_bfe_u32 v6, v40, 16, 1
	v_lshrrev_b32_e32 v5, 16, v5
	v_add3_u32 v6, v40, v6, s62
	v_and_or_b32 v36, v6, s63, v5
	v_bfe_u32 v5, v41, 16, 1
	v_add3_u32 v5, v41, v5, s62
	v_bfe_u32 v6, v42, 16, 1
	v_lshrrev_b32_e32 v5, 16, v5
	v_add3_u32 v6, v42, v6, s62
	s_lshl_b32 s16, s5, 1
	v_and_or_b32 v37, v6, s63, v5
	v_or_b32_e32 v5, s4, v33
	v_lshl_add_u64 v[38:39], v[20:21], 0, s[16:17]
	v_lshlrev_b32_e32 v6, 12, v5
	v_lshl_add_u64 v[40:41], v[38:39], 0, v[6:7]
	flat_store_dwordx4 v[40:41], v[34:37]
	ds_read_b32 v5, v55 offset:32
	ds_read_b32 v6, v55 offset:164
	ds_read_b32 v35, v55 offset:296
	ds_read_b32 v36, v55 offset:428
	ds_read_b32 v37, v55 offset:560
	ds_read_b32 v40, v55 offset:692
	ds_read_b32 v41, v55 offset:824
	ds_read_b32 v42, v55 offset:956
	s_waitcnt lgkmcnt(0)
	v_bfe_u32 v34, v5, 16, 1
	v_add3_u32 v5, v5, v34, s62
	v_bfe_u32 v34, v6, 16, 1
	v_lshrrev_b32_e32 v5, 16, v5
	v_add3_u32 v6, v6, v34, s62
	v_and_or_b32 v34, v6, s63, v5
	v_bfe_u32 v5, v35, 16, 1
	v_add3_u32 v5, v35, v5, s62
	v_bfe_u32 v6, v36, 16, 1
	v_lshrrev_b32_e32 v5, 16, v5
	v_add3_u32 v6, v36, v6, s62
	v_and_or_b32 v35, v6, s63, v5
	v_bfe_u32 v5, v37, 16, 1
	v_add3_u32 v5, v37, v5, s62
	v_bfe_u32 v6, v40, 16, 1
	v_lshrrev_b32_e32 v5, 16, v5
	v_add3_u32 v6, v40, v6, s62
	v_and_or_b32 v36, v6, s63, v5
	v_bfe_u32 v5, v41, 16, 1
	v_add3_u32 v5, v41, v5, s62
	v_bfe_u32 v6, v42, 16, 1
	v_lshrrev_b32_e32 v5, 16, v5
	v_add3_u32 v6, v42, v6, s62
	v_and_or_b32 v37, v6, s63, v5
	v_or_b32_e32 v5, s4, v56
	v_lshlrev_b32_e32 v6, 12, v5
	v_lshl_add_u64 v[40:41], v[38:39], 0, v[6:7]
	flat_store_dwordx4 v[40:41], v[34:37]
	ds_read_b32 v5, v55 offset:64
	ds_read_b32 v6, v55 offset:196
	ds_read_b32 v35, v55 offset:328
	ds_read_b32 v36, v55 offset:460
	ds_read_b32 v37, v55 offset:592
	ds_read_b32 v40, v55 offset:724
	ds_read_b32 v41, v55 offset:856
	ds_read_b32 v42, v55 offset:988
	s_waitcnt lgkmcnt(0)
	v_bfe_u32 v34, v5, 16, 1
	v_add3_u32 v5, v5, v34, s62
	v_bfe_u32 v34, v6, 16, 1
	v_lshrrev_b32_e32 v5, 16, v5
	v_add3_u32 v6, v6, v34, s62
	v_and_or_b32 v34, v6, s63, v5
	v_bfe_u32 v5, v35, 16, 1
	v_add3_u32 v5, v35, v5, s62
	v_bfe_u32 v6, v36, 16, 1
	v_lshrrev_b32_e32 v5, 16, v5
	v_add3_u32 v6, v36, v6, s62
	v_and_or_b32 v35, v6, s63, v5
	v_bfe_u32 v5, v37, 16, 1
	v_add3_u32 v5, v37, v5, s62
	v_bfe_u32 v6, v40, 16, 1
	v_lshrrev_b32_e32 v5, 16, v5
	v_add3_u32 v6, v40, v6, s62
	v_and_or_b32 v36, v6, s63, v5
	v_bfe_u32 v5, v41, 16, 1
	v_add3_u32 v5, v41, v5, s62
	v_bfe_u32 v6, v42, 16, 1
	v_lshrrev_b32_e32 v5, 16, v5
	v_add3_u32 v6, v42, v6, s62
	v_and_or_b32 v37, v6, s63, v5
	v_or_b32_e32 v5, s4, v57
	v_lshlrev_b32_e32 v6, 12, v5
	v_lshl_add_u64 v[40:41], v[38:39], 0, v[6:7]
	flat_store_dwordx4 v[40:41], v[34:37]
	ds_read_b32 v5, v55 offset:96
	ds_read_b32 v6, v55 offset:228
	ds_read_b32 v35, v55 offset:360
	ds_read_b32 v36, v55 offset:492
	ds_read_b32 v37, v55 offset:624
	ds_read_b32 v40, v55 offset:756
	ds_read_b32 v41, v55 offset:888
	ds_read_b32 v42, v55 offset:1020
	s_waitcnt lgkmcnt(0)
	v_bfe_u32 v34, v5, 16, 1
	v_add3_u32 v5, v5, v34, s62
	v_bfe_u32 v34, v6, 16, 1
	v_lshrrev_b32_e32 v5, 16, v5
	v_add3_u32 v6, v6, v34, s62
	v_and_or_b32 v34, v6, s63, v5
	v_bfe_u32 v5, v35, 16, 1
	v_add3_u32 v5, v35, v5, s62
	v_bfe_u32 v6, v36, 16, 1
	v_lshrrev_b32_e32 v5, 16, v5
	v_add3_u32 v6, v36, v6, s62
	v_and_or_b32 v35, v6, s63, v5
	v_bfe_u32 v5, v37, 16, 1
	v_add3_u32 v5, v37, v5, s62
	v_bfe_u32 v6, v40, 16, 1
	v_lshrrev_b32_e32 v5, 16, v5
	v_add3_u32 v6, v40, v6, s62
	v_and_or_b32 v36, v6, s63, v5
	v_bfe_u32 v5, v41, 16, 1
	v_add3_u32 v5, v41, v5, s62
	v_bfe_u32 v6, v42, 16, 1
	v_lshrrev_b32_e32 v5, 16, v5
	v_add3_u32 v6, v42, v6, s62
	v_and_or_b32 v37, v6, s63, v5
	v_or_b32_e32 v5, s4, v58
	v_lshlrev_b32_e32 v6, 12, v5
	v_lshl_add_u64 v[38:39], v[38:39], 0, v[6:7]
	flat_store_dwordx4 v[38:39], v[34:37]
	s_waitcnt lgkmcnt(0)
